# static priority: per-MFMA-block s_setprio flips deleted in the four GEMM K-loops, one s_setprio 1 for the trailing (waves 4-7) half per unit
# baseline (speedup 1.0000x reference)
; #define PG8_STAGE(bufoff, gbase, voff) do { _Pragma("unroll") for (int _i = 0; _i < 2; ++_i) \
;         __builtin_amdgcn_global_load_lds((const unsigned*)((const char*)(gbase) + (voff)[_i]), (PG8_LAS unsigned*)(lds + (bufoff) + ldsw + _i * 8192), 16, 0, 0); } while (0)
; #define PG8_LDA(dst, b, h) do { _Pragma("unroll") for (int m = 0; m < 4; ++m) _Pragma("unroll") for (int k = 0; k < 2; ++k) dst[m][k] = *(const PG8_LAS bf16x8*)(lds + PG8_SA(b, h) + aoff + m * 2048 + k * 1024); } while (0)
; #define PG8_LDB(dst, b, h) do { _Pragma("unroll") for (int n = 0; n < 2; ++n) _Pragma("unroll") for (int k = 0; k < 2; ++k) dst[n][k] = *(const PG8_LAS bf16x8*)(lds + PG8_SB(b, h) + boff + n * 2048 + k * 1024); } while (0)
; #define PG8_MMA(ai, bj, At, Bt) do { __builtin_amdgcn_s_setprio(1); _Pragma("unroll") for (int m = 0; m < 4; ++m) _Pragma("unroll") for (int n = 0; n < 2; ++n) _Pragma("unroll") for (int k = 0; k < 2; ++k) \
;         acc[ai][bj][m][n] = __builtin_amdgcn_mfma_f32_16x16x32_bf16(Bt[n][k], At[m][k], acc[ai][bj][m][n], 0, 0, 0); __builtin_amdgcn_s_setprio(0); } while (0)
; #define PG8_WAIT_V(n) asm volatile("s_waitcnt vmcnt(" #n ")" ::: "memory")
; template <class Epi, class Sched, bool ALIGN_EPI = false, bool SP2 = false>
; __device__ __forceinline__ void gemm_phase(PG8_LAS unsigned char* lds, const Gemm g, const Sched& S, const Epi& E) {
;     ...
;         for (int t = 0; t < nt; t += 2) {
;             const bool last = (t == nt - 2);
;             const char* a1 = cA + (size_t)(t + 1) * kstep;
;             const char* a2 = last ? nA : cA + (size_t)(t + 2) * kstep; const char* b2 = last ? nB : cB + (size_t)(t + 2) * kstep;
;             const char* a3 = a2 + kstep; const char* b3 = b2 + kstep;
;             if (last && has_next) S.a_ready(nxt);
;             if constexpr (SP2) {
;             PG8_LDB(B0, 0, 0); PG8_LDB(B1, 0, 1); PG8_SCHED; PG8_LDA(At, 0, 0); PG8_STAGE(PG8_SA(1, 1), a1 + hstep, voffA);
;             PG8_WAIT_V(8); PG8_WAIT_L(0); PG8_BAR; PG8_MMA(0, 0, At, B0); PG8_MMA(0, 1, At, B1); PG8_BAR; PG8_SCHED;
;     ...
; #pragma unroll
;         for (int a = 0; a < 2; ++a)
; #pragma unroll
;             for (int b = 0; b < 2; ++b)
; #pragma unroll
;                 for (int m = 0; m < 4; ++m)
; #pragma unroll
;                     for (int n = 0; n < 2; ++n) acc[a][b][m][n] = (f32x4){0.f, 0.f, 0.f, 0.f};
;         cur = nxt; cA = nA; cB = nB; ++ui;
.LBB0_253:
	s_ashr_i32 s43, s42, 31
	s_lshl_b64 s[6:7], s[42:43], 20
	s_add_u32 s6, s58, s6
	s_addc_u32 s7, s59, s7
	s_add_u32 s48, s6, s8
	s_addc_u32 s49, s7, s9
	s_and_b64 s[6:7], s[46:47], exec
	s_cselect_b32 s43, s49, s55
	s_cselect_b32 s53, s48, s54
	s_ashr_i32 s41, s40, 31
	s_lshl_b64 s[6:7], s[40:41], 20
	s_add_u32 s6, s60, s6
	s_addc_u32 s7, s61, s7
	s_add_u32 s50, s6, s8
	s_addc_u32 s51, s7, s9
	s_and_b64 s[6:7], s[46:47], exec
	s_cselect_b32 s8, s51, s57
	s_cselect_b32 s9, s50, s56
	s_add_i32 s41, s75, -2
	s_add_u32 s54, s54, 0x80080
	s_addc_u32 s55, s55, 0
	s_add_u32 s56, s56, 0x100
	v_mov_b32_e32 v76, 0
	s_addc_u32 s57, s57, 0
	s_mov_b32 s6, 0
	v_mov_b32_e32 v77, v76
	v_mov_b32_e32 v78, v76
	v_mov_b32_e32 v79, v76
	v_mov_b32_e32 v80, v76
	v_mov_b32_e32 v81, v76
	v_mov_b32_e32 v82, v76
	v_mov_b32_e32 v83, v76
	v_mov_b32_e32 v92, v76
	v_mov_b32_e32 v93, v76
	v_mov_b32_e32 v94, v76
	v_mov_b32_e32 v95, v76
	v_mov_b32_e32 v96, v76
	v_mov_b32_e32 v97, v76
	v_mov_b32_e32 v98, v76
	v_mov_b32_e32 v99, v76
	v_mov_b32_e32 v104, v76
	v_mov_b32_e32 v105, v76
	v_mov_b32_e32 v106, v76
	v_mov_b32_e32 v107, v76
	v_mov_b32_e32 v108, v76
	v_mov_b32_e32 v109, v76
	v_mov_b32_e32 v110, v76
	v_mov_b32_e32 v111, v76
	v_mov_b32_e32 v116, v76
	v_mov_b32_e32 v117, v76
	v_mov_b32_e32 v118, v76
	v_mov_b32_e32 v119, v76
	v_mov_b32_e32 v120, v76
	v_mov_b32_e32 v121, v76
	v_mov_b32_e32 v122, v76
	v_mov_b32_e32 v123, v76
	v_mov_b32_e32 v88, v76
	v_mov_b32_e32 v89, v76
	v_mov_b32_e32 v90, v76
	v_mov_b32_e32 v91, v76
	v_mov_b32_e32 v0, v76
	v_mov_b32_e32 v1, v76
	v_mov_b32_e32 v2, v76
	v_mov_b32_e32 v3, v76
	v_mov_b32_e32 v100, v76
	v_mov_b32_e32 v101, v76
	v_mov_b32_e32 v102, v76
	v_mov_b32_e32 v103, v76
	v_mov_b32_e32 v4, v76
	v_mov_b32_e32 v5, v76
	v_mov_b32_e32 v6, v76
	v_mov_b32_e32 v7, v76
	v_mov_b32_e32 v112, v76
	v_mov_b32_e32 v113, v76
	v_mov_b32_e32 v114, v76
	v_mov_b32_e32 v115, v76
	v_mov_b32_e32 v8, v76
	v_mov_b32_e32 v9, v76
	v_mov_b32_e32 v10, v76
	v_mov_b32_e32 v11, v76
	v_mov_b32_e32 v124, v76
	v_mov_b32_e32 v125, v76
	v_mov_b32_e32 v126, v76
	v_mov_b32_e32 v127, v76
	v_mov_b32_e32 v12, v76
	v_mov_b32_e32 v13, v76
	v_mov_b32_e32 v14, v76
	v_mov_b32_e32 v15, v76
	v_mov_b32_e32 v24, v76
	v_mov_b32_e32 v25, v76
	v_mov_b32_e32 v26, v76
	v_mov_b32_e32 v27, v76
	v_mov_b32_e32 v32, v76
	v_mov_b32_e32 v33, v76
	v_mov_b32_e32 v34, v76
	v_mov_b32_e32 v35, v76
	v_mov_b32_e32 v44, v76
	v_mov_b32_e32 v45, v76
	v_mov_b32_e32 v46, v76
	v_mov_b32_e32 v47, v76
	v_mov_b32_e32 v48, v76
	v_mov_b32_e32 v49, v76
	v_mov_b32_e32 v50, v76
	v_mov_b32_e32 v51, v76
	v_mov_b32_e32 v56, v76
	v_mov_b32_e32 v57, v76
	v_mov_b32_e32 v58, v76
	v_mov_b32_e32 v59, v76
	v_mov_b32_e32 v60, v76
	v_mov_b32_e32 v61, v76
	v_mov_b32_e32 v62, v76
	v_mov_b32_e32 v63, v76
	v_mov_b32_e32 v68, v76
	v_mov_b32_e32 v69, v76
	v_mov_b32_e32 v70, v76
	v_mov_b32_e32 v71, v76
	v_mov_b32_e32 v72, v76
	v_mov_b32_e32 v73, v76
	v_mov_b32_e32 v74, v76
	v_mov_b32_e32 v75, v76
	v_mov_b32_e32 v40, v76
	v_mov_b32_e32 v41, v76
	v_mov_b32_e32 v42, v76
	v_mov_b32_e32 v43, v76
	v_mov_b32_e32 v16, v76
	v_mov_b32_e32 v17, v76
	v_mov_b32_e32 v18, v76
	v_mov_b32_e32 v19, v76
	v_mov_b32_e32 v52, v76
	v_mov_b32_e32 v53, v76
	v_mov_b32_e32 v54, v76
	v_mov_b32_e32 v55, v76
	v_mov_b32_e32 v20, v76
	v_mov_b32_e32 v21, v76
	v_mov_b32_e32 v22, v76
	v_mov_b32_e32 v23, v76
	v_mov_b32_e32 v64, v76
	v_mov_b32_e32 v65, v76
	v_mov_b32_e32 v66, v76
	v_mov_b32_e32 v67, v76
	v_mov_b32_e32 v28, v76
	v_mov_b32_e32 v29, v76
	v_mov_b32_e32 v30, v76
	v_mov_b32_e32 v31, v76
	v_mov_b32_e32 v84, v76
	v_mov_b32_e32 v85, v76
	v_mov_b32_e32 v86, v76
	v_mov_b32_e32 v87, v76
	v_mov_b32_e32 v36, v76
	v_mov_b32_e32 v37, v76
	v_mov_b32_e32 v38, v76
	v_mov_b32_e32 v39, v76
	s_cmp_eq_u32 s62, 1
	s_cbranch_scc0 .Lprio_skip_0
	s_setprio 1
.Lprio_skip_0:
.LBB0_254:
	s_add_i32 s77, s6, 2
	s_add_u32 s30, s54, 0xfff80080
	s_addc_u32 s7, s55, -1
	s_add_i32 s78, 0, 0x10000
	s_cmp_eq_u32 s41, s6
	s_cselect_b32 s7, s43, s7
	s_cselect_b32 s6, s53, s30
	v_add_u32_e32 v144, s78, v151
	s_cselect_b32 s31, s8, s57
	s_cselect_b32 s30, s9, s56
	s_add_i32 s80, 0, 0x14000
	ds_read_b128 v[128:131], v144
	ds_read_b128 v[132:135], v144 offset:1024
	ds_read_b128 v[154:157], v144 offset:2048
	ds_read_b128 v[158:161], v144 offset:3072
	v_add_u32_e32 v144, s80, v151
	ds_read_b128 v[162:165], v144
	ds_read_b128 v[178:181], v144 offset:1024
	ds_read_b128 v[182:185], v144 offset:2048
	ds_read_b128 v[186:189], v144 offset:3072
	v_lshl_add_u64 v[144:145], s[54:55], 0, v[140:141]
	s_add_i32 m0, s45, 0xc000
	ds_read_b128 v[190:193], v153
	ds_read_b128 v[194:197], v153 offset:1024
	ds_read_b128 v[198:201], v153 offset:2048
	ds_read_b128 v[202:205], v153 offset:3072
	ds_read_b128 v[206:209], v153 offset:4096
	ds_read_b128 v[226:229], v153 offset:5120
	ds_read_b128 v[230:233], v153 offset:6144
	ds_read_b128 v[234:237], v153 offset:7168
	global_load_lds_dwordx4 v[144:145], off
	v_lshl_add_u64 v[144:145], s[54:55], 0, v[142:143]
	s_add_i32 m0, s45, 0xe000
	s_nop 0
	global_load_lds_dwordx4 v[144:145], off
	s_waitcnt vmcnt(8)
	s_waitcnt lgkmcnt(0)
	s_barrier
; #define PG8_STAGE(bufoff, gbase, voff) do { _Pragma("unroll") for (int _i = 0; _i < 2; ++_i) \
;         __builtin_amdgcn_global_load_lds((const unsigned*)((const char*)(gbase) + (voff)[_i]), (PG8_LAS unsigned*)(lds + (bufoff) + ldsw + _i * 8192), 16, 0, 0); } while (0)
; #define PG8_LDA(dst, b, h) do { _Pragma("unroll") for (int m = 0; m < 4; ++m) _Pragma("unroll") for (int k = 0; k < 2; ++k) dst[m][k] = *(const PG8_LAS bf16x8*)(lds + PG8_SA(b, h) + aoff + m * 2048 + k * 1024); } while (0)
; #define PG8_MMA(ai, bj, At, Bt) do { __builtin_amdgcn_s_setprio(1); _Pragma("unroll") for (int m = 0; m < 4; ++m) _Pragma("unroll") for (int n = 0; n < 2; ++n) _Pragma("unroll") for (int k = 0; k < 2; ++k) \
;         acc[ai][bj][m][n] = __builtin_amdgcn_mfma_f32_16x16x32_bf16(Bt[n][k], At[m][k], acc[ai][bj][m][n], 0, 0, 0); __builtin_amdgcn_s_setprio(0); } while (0)
; #define PG8_WAIT_V(n) asm volatile("s_waitcnt vmcnt(" #n ")" ::: "memory")
; #define PG8_WAIT_L(n) asm volatile("s_waitcnt lgkmcnt(" #n ")" ::: "memory")
; #define PG8_BAR __builtin_amdgcn_s_barrier()
; #define PG8_SCHED __builtin_amdgcn_sched_barrier(0)
; template <class Epi, class Sched, bool ALIGN_EPI = false, bool SP2 = false>
; __device__ __forceinline__ void gemm_phase(PG8_LAS unsigned char* lds, const Gemm g, const Sched& S, const Epi& E) {
;     ...
;             PG8_WAIT_V(8); PG8_WAIT_L(0); PG8_BAR; PG8_MMA(0, 0, At, B0); PG8_MMA(0, 1, At, B1); PG8_BAR; PG8_SCHED;
;             PG8_LDA(At, 0, 1); PG8_STAGE(PG8_SB(0, 0), b2, voffB); PG8_STAGE(PG8_SB(0, 1), b2 + hstep, voffB); PG8_STAGE(PG8_SA(0, 0), a2, voffA);
;             PG8_WAIT_V(8); PG8_WAIT_L(0); PG8_BAR; PG8_MMA(1, 0, At, B0); PG8_MMA(1, 1, At, B1); PG8_BAR; PG8_SCHED;
	s_waitcnt lgkmcnt(0)
	v_mfma_f32_16x16x32_bf16 v[36:39], v[128:131], v[190:193], v[36:39]
	v_mfma_f32_16x16x32_bf16 v[84:87], v[154:157], v[190:193], v[84:87]
	v_mfma_f32_16x16x32_bf16 v[28:31], v[128:131], v[198:201], v[28:31]
	v_mfma_f32_16x16x32_bf16 v[64:67], v[154:157], v[198:201], v[64:67]
	v_mfma_f32_16x16x32_bf16 v[20:23], v[128:131], v[206:209], v[20:23]
	v_mfma_f32_16x16x32_bf16 v[52:55], v[154:157], v[206:209], v[52:55]
	v_mfma_f32_16x16x32_bf16 v[16:19], v[128:131], v[230:233], v[16:19]
	v_mfma_f32_16x16x32_bf16 v[40:43], v[154:157], v[230:233], v[40:43]
	v_mfma_f32_16x16x32_bf16 v[36:39], v[132:135], v[194:197], v[36:39]
	v_mfma_f32_16x16x32_bf16 v[84:87], v[158:161], v[194:197], v[84:87]
	v_mfma_f32_16x16x32_bf16 v[28:31], v[132:135], v[202:205], v[28:31]
	v_mfma_f32_16x16x32_bf16 v[64:67], v[158:161], v[202:205], v[64:67]
	v_mfma_f32_16x16x32_bf16 v[20:23], v[132:135], v[226:229], v[20:23]
	v_mfma_f32_16x16x32_bf16 v[52:55], v[158:161], v[226:229], v[52:55]
	v_mfma_f32_16x16x32_bf16 v[16:19], v[132:135], v[234:237], v[16:19]
	v_mfma_f32_16x16x32_bf16 v[40:43], v[158:161], v[234:237], v[40:43]
	v_mfma_f32_16x16x32_bf16 v[72:75], v[162:165], v[190:193], v[72:75]
	v_mfma_f32_16x16x32_bf16 v[68:71], v[182:185], v[190:193], v[68:71]
	v_mfma_f32_16x16x32_bf16 v[60:63], v[162:165], v[198:201], v[60:63]
	v_mfma_f32_16x16x32_bf16 v[56:59], v[182:185], v[198:201], v[56:59]
	v_mfma_f32_16x16x32_bf16 v[48:51], v[162:165], v[206:209], v[48:51]
	v_mfma_f32_16x16x32_bf16 v[44:47], v[182:185], v[206:209], v[44:47]
	v_mfma_f32_16x16x32_bf16 v[32:35], v[162:165], v[230:233], v[32:35]
	v_mfma_f32_16x16x32_bf16 v[24:27], v[182:185], v[230:233], v[24:27]
	v_mfma_f32_16x16x32_bf16 v[72:75], v[178:181], v[194:197], v[72:75]
	v_mfma_f32_16x16x32_bf16 v[68:71], v[186:189], v[194:197], v[68:71]
	v_mfma_f32_16x16x32_bf16 v[60:63], v[178:181], v[202:205], v[60:63]
	v_mfma_f32_16x16x32_bf16 v[56:59], v[186:189], v[202:205], v[56:59]
	v_mfma_f32_16x16x32_bf16 v[48:51], v[178:181], v[226:229], v[48:51]
	v_mfma_f32_16x16x32_bf16 v[44:47], v[186:189], v[226:229], v[44:47]
	v_mfma_f32_16x16x32_bf16 v[32:35], v[178:181], v[234:237], v[32:35]
	v_mfma_f32_16x16x32_bf16 v[24:27], v[186:189], v[234:237], v[24:27]
	s_barrier
	s_add_i32 s78, s78, s63
	v_lshl_add_u64 v[144:145], s[30:31], 0, v[136:137]
	s_mov_b32 m0, s78
	ds_read_b128 v[190:193], v153 offset:16384
	ds_read_b128 v[194:197], v153 offset:17408
	ds_read_b128 v[198:201], v153 offset:18432
	ds_read_b128 v[202:205], v153 offset:19456
	ds_read_b128 v[206:209], v153 offset:20480
	ds_read_b128 v[226:229], v153 offset:21504
	ds_read_b128 v[230:233], v153 offset:22528
	ds_read_b128 v[234:237], v153 offset:23552
	global_load_lds_dwordx4 v[144:145], off
	s_add_i32 m0, s78, 0x2000
	s_add_u32 s78, s30, 0x80000
	v_lshl_add_u64 v[166:167], s[30:31], 0, v[138:139]
	s_addc_u32 s79, s31, 0
	s_add_i32 s80, s80, s63
	global_load_lds_dwordx4 v[166:167], off
	v_lshl_add_u64 v[238:239], s[78:79], 0, v[136:137]
	s_mov_b32 m0, s80
	v_lshl_add_u64 v[240:241], s[6:7], 0, v[138:139]
	global_load_lds_dwordx4 v[238:239], off
	v_lshl_add_u64 v[238:239], s[78:79], 0, v[138:139]
	s_add_i32 m0, s80, 0x2000
	s_nop 0
	global_load_lds_dwordx4 v[238:239], off
	v_lshl_add_u64 v[238:239], s[6:7], 0, v[136:137]
	s_mov_b32 m0, s45
	s_nop 0
	global_load_lds_dwordx4 v[238:239], off
	s_mov_b32 m0, s64
	s_nop 0
	global_load_lds_dwordx4 v[240:241], off
	s_waitcnt vmcnt(8)
	s_waitcnt lgkmcnt(0)
	s_barrier
	s_waitcnt lgkmcnt(0)
	v_mfma_f32_16x16x32_bf16 v[12:15], v[128:131], v[190:193], v[12:15]
	v_mfma_f32_16x16x32_bf16 v[124:127], v[154:157], v[190:193], v[124:127]
	v_mfma_f32_16x16x32_bf16 v[8:11], v[128:131], v[198:201], v[8:11]
	v_mfma_f32_16x16x32_bf16 v[112:115], v[154:157], v[198:201], v[112:115]
	v_mfma_f32_16x16x32_bf16 v[4:7], v[128:131], v[206:209], v[4:7]
	v_mfma_f32_16x16x32_bf16 v[100:103], v[154:157], v[206:209], v[100:103]
	v_mfma_f32_16x16x32_bf16 v[0:3], v[128:131], v[230:233], v[0:3]
	v_mfma_f32_16x16x32_bf16 v[88:91], v[154:157], v[230:233], v[88:91]
	v_mfma_f32_16x16x32_bf16 v[12:15], v[132:135], v[194:197], v[12:15]
	v_mfma_f32_16x16x32_bf16 v[124:127], v[158:161], v[194:197], v[124:127]
	v_mfma_f32_16x16x32_bf16 v[8:11], v[132:135], v[202:205], v[8:11]
	v_mfma_f32_16x16x32_bf16 v[112:115], v[158:161], v[202:205], v[112:115]
	v_mfma_f32_16x16x32_bf16 v[4:7], v[132:135], v[226:229], v[4:7]
	v_mfma_f32_16x16x32_bf16 v[100:103], v[158:161], v[226:229], v[100:103]
	v_mfma_f32_16x16x32_bf16 v[0:3], v[132:135], v[234:237], v[0:3]
	v_mfma_f32_16x16x32_bf16 v[88:91], v[158:161], v[234:237], v[88:91]
	v_mfma_f32_16x16x32_bf16 v[120:123], v[162:165], v[190:193], v[120:123]
	v_mfma_f32_16x16x32_bf16 v[116:119], v[182:185], v[190:193], v[116:119]
	v_mfma_f32_16x16x32_bf16 v[108:111], v[162:165], v[198:201], v[108:111]
	v_mfma_f32_16x16x32_bf16 v[104:107], v[182:185], v[198:201], v[104:107]
	v_mfma_f32_16x16x32_bf16 v[96:99], v[162:165], v[206:209], v[96:99]
	v_mfma_f32_16x16x32_bf16 v[92:95], v[182:185], v[206:209], v[92:95]
	v_mfma_f32_16x16x32_bf16 v[80:83], v[162:165], v[230:233], v[80:83]
	v_mfma_f32_16x16x32_bf16 v[76:79], v[182:185], v[230:233], v[76:79]
	v_mfma_f32_16x16x32_bf16 v[120:123], v[178:181], v[194:197], v[120:123]
	v_mfma_f32_16x16x32_bf16 v[116:119], v[186:189], v[194:197], v[116:119]
	v_mfma_f32_16x16x32_bf16 v[108:111], v[178:181], v[202:205], v[108:111]
	v_mfma_f32_16x16x32_bf16 v[104:107], v[186:189], v[202:205], v[104:107]
	v_mfma_f32_16x16x32_bf16 v[96:99], v[178:181], v[226:229], v[96:99]
	v_mfma_f32_16x16x32_bf16 v[92:95], v[186:189], v[226:229], v[92:95]
	v_mfma_f32_16x16x32_bf16 v[80:83], v[178:181], v[234:237], v[80:83]
	v_mfma_f32_16x16x32_bf16 v[76:79], v[186:189], v[234:237], v[76:79]
	s_barrier
; #define PG8_STAGE(bufoff, gbase, voff) do { _Pragma("unroll") for (int _i = 0; _i < 2; ++_i) \
;         __builtin_amdgcn_global_load_lds((const unsigned*)((const char*)(gbase) + (voff)[_i]), (PG8_LAS unsigned*)(lds + (bufoff) + ldsw + _i * 8192), 16, 0, 0); } while (0)
; #define PG8_LDA(dst, b, h) do { _Pragma("unroll") for (int m = 0; m < 4; ++m) _Pragma("unroll") for (int k = 0; k < 2; ++k) dst[m][k] = *(const PG8_LAS bf16x8*)(lds + PG8_SA(b, h) + aoff + m * 2048 + k * 1024); } while (0)
; #define PG8_LDB(dst, b, h) do { _Pragma("unroll") for (int n = 0; n < 2; ++n) _Pragma("unroll") for (int k = 0; k < 2; ++k) dst[n][k] = *(const PG8_LAS bf16x8*)(lds + PG8_SB(b, h) + boff + n * 2048 + k * 1024); } while (0)
; #define PG8_MMA(ai, bj, At, Bt) do { __builtin_amdgcn_s_setprio(1); _Pragma("unroll") for (int m = 0; m < 4; ++m) _Pragma("unroll") for (int n = 0; n < 2; ++n) _Pragma("unroll") for (int k = 0; k < 2; ++k) \
;         acc[ai][bj][m][n] = __builtin_amdgcn_mfma_f32_16x16x32_bf16(Bt[n][k], At[m][k], acc[ai][bj][m][n], 0, 0, 0); __builtin_amdgcn_s_setprio(0); } while (0)
; #define PG8_WAIT_V(n) asm volatile("s_waitcnt vmcnt(" #n ")" ::: "memory")
; #define PG8_WAIT_L(n) asm volatile("s_waitcnt lgkmcnt(" #n ")" ::: "memory")
; #define PG8_BAR __builtin_amdgcn_s_barrier()
; #define PG8_SCHED __builtin_amdgcn_sched_barrier(0)
; template <class Epi, class Sched, bool ALIGN_EPI = false, bool SP2 = false>
; __device__ __forceinline__ void gemm_phase(PG8_LAS unsigned char* lds, const Gemm g, const Sched& S, const Epi& E) {
;     ...
;             PG8_LDB(B0, 1, 0); PG8_LDB(B1, 1, 1); PG8_SCHED; PG8_LDA(At, 1, 0); PG8_STAGE(PG8_SA(0, 1), a2 + hstep, voffA);
;             PG8_WAIT_V(8); PG8_WAIT_L(0); PG8_BAR; PG8_MMA(0, 0, At, B0); PG8_MMA(0, 1, At, B1); PG8_BAR; PG8_SCHED;
	s_add_i32 s78, 0, 0x18000
	v_add_u32_e32 v146, s78, v151
	s_add_i32 s79, 0, 0x1c000
	ds_read_b128 v[128:131], v146
	ds_read_b128 v[132:135], v146 offset:1024
	ds_read_b128 v[154:157], v146 offset:2048
	ds_read_b128 v[158:161], v146 offset:3072
	v_add_u32_e32 v146, s79, v151
	ds_read_b128 v[162:165], v146
	ds_read_b128 v[178:181], v146 offset:1024
	ds_read_b128 v[182:185], v146 offset:2048
	ds_read_b128 v[186:189], v146 offset:3072
	s_add_u32 s6, s6, 0x80000
	s_addc_u32 s7, s7, 0
	s_mov_b32 m0, s65
	v_lshl_add_u64 v[242:243], s[6:7], 0, v[136:137]
	ds_read_b128 v[190:193], v153 offset:32768
	ds_read_b128 v[194:197], v153 offset:33792
	ds_read_b128 v[198:201], v153 offset:34816
	ds_read_b128 v[202:205], v153 offset:35840
	ds_read_b128 v[206:209], v153 offset:36864
	ds_read_b128 v[226:229], v153 offset:37888
	ds_read_b128 v[230:233], v153 offset:38912
	ds_read_b128 v[234:237], v153 offset:39936
	global_load_lds_dwordx4 v[242:243], off
	v_lshl_add_u64 v[242:243], s[6:7], 0, v[138:139]
	s_mov_b32 m0, s66
	s_nop 0
	global_load_lds_dwordx4 v[242:243], off
	s_waitcnt vmcnt(8)
	s_waitcnt lgkmcnt(0)
	s_barrier
	s_waitcnt lgkmcnt(0)
	v_mfma_f32_16x16x32_bf16 v[36:39], v[128:131], v[190:193], v[36:39]
	v_mfma_f32_16x16x32_bf16 v[84:87], v[154:157], v[190:193], v[84:87]
	v_mfma_f32_16x16x32_bf16 v[28:31], v[128:131], v[198:201], v[28:31]
	v_mfma_f32_16x16x32_bf16 v[64:67], v[154:157], v[198:201], v[64:67]
	v_mfma_f32_16x16x32_bf16 v[20:23], v[128:131], v[206:209], v[20:23]
	v_mfma_f32_16x16x32_bf16 v[52:55], v[154:157], v[206:209], v[52:55]
	v_mfma_f32_16x16x32_bf16 v[16:19], v[128:131], v[230:233], v[16:19]
	v_mfma_f32_16x16x32_bf16 v[40:43], v[154:157], v[230:233], v[40:43]
	v_mfma_f32_16x16x32_bf16 v[36:39], v[132:135], v[194:197], v[36:39]
	v_mfma_f32_16x16x32_bf16 v[84:87], v[158:161], v[194:197], v[84:87]
	v_mfma_f32_16x16x32_bf16 v[28:31], v[132:135], v[202:205], v[28:31]
	v_mfma_f32_16x16x32_bf16 v[64:67], v[158:161], v[202:205], v[64:67]
	v_mfma_f32_16x16x32_bf16 v[20:23], v[132:135], v[226:229], v[20:23]
	v_mfma_f32_16x16x32_bf16 v[52:55], v[158:161], v[226:229], v[52:55]
	v_mfma_f32_16x16x32_bf16 v[16:19], v[132:135], v[234:237], v[16:19]
	v_mfma_f32_16x16x32_bf16 v[40:43], v[158:161], v[234:237], v[40:43]
	v_mfma_f32_16x16x32_bf16 v[72:75], v[162:165], v[190:193], v[72:75]
	v_mfma_f32_16x16x32_bf16 v[68:71], v[182:185], v[190:193], v[68:71]
	v_mfma_f32_16x16x32_bf16 v[60:63], v[162:165], v[198:201], v[60:63]
	v_mfma_f32_16x16x32_bf16 v[56:59], v[182:185], v[198:201], v[56:59]
	v_mfma_f32_16x16x32_bf16 v[48:51], v[162:165], v[206:209], v[48:51]
	v_mfma_f32_16x16x32_bf16 v[44:47], v[182:185], v[206:209], v[44:47]
	v_mfma_f32_16x16x32_bf16 v[32:35], v[162:165], v[230:233], v[32:35]
	v_mfma_f32_16x16x32_bf16 v[24:27], v[182:185], v[230:233], v[24:27]
	v_mfma_f32_16x16x32_bf16 v[72:75], v[178:181], v[194:197], v[72:75]
	v_mfma_f32_16x16x32_bf16 v[68:71], v[186:189], v[194:197], v[68:71]
	v_mfma_f32_16x16x32_bf16 v[60:63], v[178:181], v[202:205], v[60:63]
	v_mfma_f32_16x16x32_bf16 v[56:59], v[186:189], v[202:205], v[56:59]
	v_mfma_f32_16x16x32_bf16 v[48:51], v[178:181], v[226:229], v[48:51]
	v_mfma_f32_16x16x32_bf16 v[44:47], v[186:189], v[226:229], v[44:47]
	v_mfma_f32_16x16x32_bf16 v[32:35], v[178:181], v[234:237], v[32:35]
	v_mfma_f32_16x16x32_bf16 v[24:27], v[186:189], v[234:237], v[24:27]
	s_barrier
; #define PG8_STAGE(bufoff, gbase, voff) do { _Pragma("unroll") for (int _i = 0; _i < 2; ++_i) \
;         __builtin_amdgcn_global_load_lds((const unsigned*)((const char*)(gbase) + (voff)[_i]), (PG8_LAS unsigned*)(lds + (bufoff) + ldsw + _i * 8192), 16, 0, 0); } while (0)
; #define PG8_LDA(dst, b, h) do { _Pragma("unroll") for (int m = 0; m < 4; ++m) _Pragma("unroll") for (int k = 0; k < 2; ++k) dst[m][k] = *(const PG8_LAS bf16x8*)(lds + PG8_SA(b, h) + aoff + m * 2048 + k * 1024); } while (0)
; #define PG8_MMA(ai, bj, At, Bt) do { __builtin_amdgcn_s_setprio(1); _Pragma("unroll") for (int m = 0; m < 4; ++m) _Pragma("unroll") for (int n = 0; n < 2; ++n) _Pragma("unroll") for (int k = 0; k < 2; ++k) \
;         acc[ai][bj][m][n] = __builtin_amdgcn_mfma_f32_16x16x32_bf16(Bt[n][k], At[m][k], acc[ai][bj][m][n], 0, 0, 0); __builtin_amdgcn_s_setprio(0); } while (0)
; #define PG8_WAIT_V(n) asm volatile("s_waitcnt vmcnt(" #n ")" ::: "memory")
; #define PG8_WAIT_L(n) asm volatile("s_waitcnt lgkmcnt(" #n ")" ::: "memory")
; #define PG8_BAR __builtin_amdgcn_s_barrier()
; #define PG8_SCHED __builtin_amdgcn_sched_barrier(0)
; template <class Epi, class Sched, bool ALIGN_EPI = false, bool SP2 = false>
; __device__ __forceinline__ void gemm_phase(PG8_LAS unsigned char* lds, const Gemm g, const Sched& S, const Epi& E) {
;     ...
;         for (int t = 0; t < nt; t += 2) {
;     ...
;             PG8_LDA(At, 1, 1); PG8_STAGE(PG8_SB(1, 0), b3, voffB); PG8_STAGE(PG8_SB(1, 1), b3 + hstep, voffB); PG8_STAGE(PG8_SA(1, 0), a3, voffA);
;             PG8_WAIT_V(8); PG8_WAIT_L(0); PG8_BAR; PG8_MMA(1, 0, At, B0); PG8_MMA(1, 1, At, B1); PG8_BAR; PG8_SCHED;
	s_add_i32 s6, s78, s63
	v_lshl_add_u64 v[144:145], v[144:145], 0, s[20:21]
	s_mov_b32 m0, s6
	ds_read_b128 v[190:193], v153 offset:49152
	ds_read_b128 v[194:197], v153 offset:50176
	ds_read_b128 v[198:201], v153 offset:51200
	ds_read_b128 v[202:205], v153 offset:52224
	ds_read_b128 v[206:209], v153 offset:53248
	ds_read_b128 v[226:229], v153 offset:54272
	ds_read_b128 v[230:233], v153 offset:55296
	ds_read_b128 v[234:237], v153 offset:56320
	global_load_lds_dwordx4 v[144:145], off
	s_add_i32 m0, s6, 0x2000
	s_add_u32 s6, s30, 0x80080
	v_lshl_add_u64 v[144:145], v[166:167], 0, s[20:21]
	s_addc_u32 s7, s31, 0
	s_add_i32 s30, s79, s63
	global_load_lds_dwordx4 v[144:145], off
	v_lshl_add_u64 v[144:145], s[6:7], 0, v[136:137]
	s_mov_b32 m0, s30
	s_nop 0
	global_load_lds_dwordx4 v[144:145], off
	v_lshl_add_u64 v[144:145], s[6:7], 0, v[138:139]
	s_add_i32 m0, s30, 0x2000
	s_nop 0
	global_load_lds_dwordx4 v[144:145], off
	v_lshl_add_u64 v[144:145], v[238:239], 0, s[20:21]
	s_mov_b32 m0, s68
	s_nop 0
	global_load_lds_dwordx4 v[144:145], off
	v_lshl_add_u64 v[144:145], v[240:241], 0, s[20:21]
	s_mov_b32 m0, s69
	s_nop 0
	global_load_lds_dwordx4 v[144:145], off
	s_waitcnt vmcnt(8)
	s_waitcnt lgkmcnt(0)
	s_barrier
	s_waitcnt lgkmcnt(0)
	v_mfma_f32_16x16x32_bf16 v[12:15], v[128:131], v[190:193], v[12:15]
	v_mfma_f32_16x16x32_bf16 v[124:127], v[154:157], v[190:193], v[124:127]
	v_mfma_f32_16x16x32_bf16 v[8:11], v[128:131], v[198:201], v[8:11]
	v_mfma_f32_16x16x32_bf16 v[112:115], v[154:157], v[198:201], v[112:115]
	v_mfma_f32_16x16x32_bf16 v[4:7], v[128:131], v[206:209], v[4:7]
	v_mfma_f32_16x16x32_bf16 v[100:103], v[154:157], v[206:209], v[100:103]
	v_mfma_f32_16x16x32_bf16 v[0:3], v[128:131], v[230:233], v[0:3]
	v_mfma_f32_16x16x32_bf16 v[88:91], v[154:157], v[230:233], v[88:91]
	v_mfma_f32_16x16x32_bf16 v[12:15], v[132:135], v[194:197], v[12:15]
	v_mfma_f32_16x16x32_bf16 v[124:127], v[158:161], v[194:197], v[124:127]
	v_mfma_f32_16x16x32_bf16 v[8:11], v[132:135], v[202:205], v[8:11]
	v_mfma_f32_16x16x32_bf16 v[112:115], v[158:161], v[202:205], v[112:115]
	v_mfma_f32_16x16x32_bf16 v[4:7], v[132:135], v[226:229], v[4:7]
	v_mfma_f32_16x16x32_bf16 v[100:103], v[158:161], v[226:229], v[100:103]
	v_mfma_f32_16x16x32_bf16 v[0:3], v[132:135], v[234:237], v[0:3]
	v_mfma_f32_16x16x32_bf16 v[88:91], v[158:161], v[234:237], v[88:91]
	v_mfma_f32_16x16x32_bf16 v[120:123], v[162:165], v[190:193], v[120:123]
	v_mfma_f32_16x16x32_bf16 v[116:119], v[182:185], v[190:193], v[116:119]
	v_mfma_f32_16x16x32_bf16 v[108:111], v[162:165], v[198:201], v[108:111]
	v_mfma_f32_16x16x32_bf16 v[104:107], v[182:185], v[198:201], v[104:107]
	v_mfma_f32_16x16x32_bf16 v[96:99], v[162:165], v[206:209], v[96:99]
	v_mfma_f32_16x16x32_bf16 v[92:95], v[182:185], v[206:209], v[92:95]
	v_mfma_f32_16x16x32_bf16 v[80:83], v[162:165], v[230:233], v[80:83]
	v_mfma_f32_16x16x32_bf16 v[76:79], v[182:185], v[230:233], v[76:79]
	v_mfma_f32_16x16x32_bf16 v[120:123], v[178:181], v[194:197], v[120:123]
	v_mfma_f32_16x16x32_bf16 v[116:119], v[186:189], v[194:197], v[116:119]
	v_mfma_f32_16x16x32_bf16 v[108:111], v[178:181], v[202:205], v[108:111]
	v_mfma_f32_16x16x32_bf16 v[104:107], v[186:189], v[202:205], v[104:107]
	v_mfma_f32_16x16x32_bf16 v[96:99], v[178:181], v[226:229], v[96:99]
	v_mfma_f32_16x16x32_bf16 v[92:95], v[186:189], v[226:229], v[92:95]
	v_mfma_f32_16x16x32_bf16 v[80:83], v[178:181], v[234:237], v[80:83]
	v_mfma_f32_16x16x32_bf16 v[76:79], v[186:189], v[234:237], v[76:79]
	s_barrier
	s_add_u32 s54, s54, 0x100
	s_addc_u32 s55, s55, 0
	s_add_u32 s56, s56, 0x100
	s_addc_u32 s57, s57, 0
	s_cmp_ge_u32 s77, s75
	s_mov_b32 s6, s77
	s_cbranch_scc0 .LBB0_254
	s_setprio 0
	s_and_b64 vcc, exec, s[38:39]
	s_cbranch_vccz .LBB0_257
	s_barrier

; #define PG8_STAGE(bufoff, gbase, voff) do { _Pragma("unroll") for (int _i = 0; _i < 2; ++_i) \
;         __builtin_amdgcn_global_load_lds((const unsigned*)((const char*)(gbase) + (voff)[_i]), (PG8_LAS unsigned*)(lds + (bufoff) + ldsw + _i * 8192), 16, 0, 0); } while (0)
; #define PG8_LDA(dst, b, h) do { _Pragma("unroll") for (int m = 0; m < 4; ++m) _Pragma("unroll") for (int k = 0; k < 2; ++k) dst[m][k] = *(const PG8_LAS bf16x8*)(lds + PG8_SA(b, h) + aoff + m * 2048 + k * 1024); } while (0)
; #define PG8_LDB(dst, b, h) do { _Pragma("unroll") for (int n = 0; n < 2; ++n) _Pragma("unroll") for (int k = 0; k < 2; ++k) dst[n][k] = *(const PG8_LAS bf16x8*)(lds + PG8_SB(b, h) + boff + n * 2048 + k * 1024); } while (0)
; #define PG8_SCHED __builtin_amdgcn_sched_barrier(0)
; template <class Epi, class Sched, bool ALIGN_EPI = false, bool SP2 = false>
; __device__ __forceinline__ void gemm_phase(PG8_LAS unsigned char* lds, const Gemm g, const Sched& S, const Epi& E) {
;     ...
;         const bool has_next = S.next(ui + 1, nxt);
;         const char* nA = has_next ? (const char*)g.A + (size_t)nxt.pm * tstep + (size_t)nxt.k0 * kstep : cA; const char* nB = has_next ? (const char*)g.Bt + (size_t)nxt.pn * tstep + (size_t)nxt.k0 * kstep : cB;
;         const int nt = cur.nt;
;         for (int t = 0; t < nt; t += 2) {
;             const bool last = (t == nt - 2);
;             const char* a1 = cA + (size_t)(t + 1) * kstep;
;             const char* a2 = last ? nA : cA + (size_t)(t + 2) * kstep; const char* b2 = last ? nB : cB + (size_t)(t + 2) * kstep;
;             const char* a3 = a2 + kstep; const char* b3 = b2 + kstep;
;             if (last && has_next) S.a_ready(nxt);
;             if constexpr (SP2) {
;             PG8_LDB(B0, 0, 0); PG8_LDB(B1, 0, 1); PG8_SCHED; PG8_LDA(At, 0, 0); PG8_STAGE(PG8_SA(1, 1), a1 + hstep, voffA);
;     ...
;         for (int a = 0; a < 2; ++a)
; #pragma unroll
;             for (int b = 0; b < 2; ++b)
; #pragma unroll
;                 for (int m = 0; m < 4; ++m)
; #pragma unroll
;                     for (int n = 0; n < 2; ++n) acc[a][b][m][n] = (f32x4){0.f, 0.f, 0.f, 0.f};
.LBB0_559:
	s_ashr_i32 s49, s48, 31
	s_lshl_b64 s[30:31], s[48:49], 20
	s_add_u32 s10, s60, s30
	s_addc_u32 s30, s61, s31
	s_add_u32 s50, s10, s6
	s_addc_u32 s51, s30, s7
	s_and_b64 s[30:31], s[46:47], exec
	s_cselect_b32 s10, s51, s43
	s_cselect_b32 s41, s50, s42
	s_ashr_i32 s45, s44, 31
	s_lshl_b64 s[30:31], s[44:45], 20
	s_add_u32 s30, s62, s30
	s_addc_u32 s31, s63, s31
	s_add_u32 s52, s30, s6
	s_addc_u32 s53, s31, s7
	s_and_b64 s[6:7], s[46:47], exec
	s_cselect_b32 s45, s53, s55
	s_cselect_b32 s49, s52, s54
	s_add_i32 s56, s5, -2
	s_add_u32 s42, s42, 0x80080
	s_addc_u32 s43, s43, 0
	s_add_u32 s54, s54, 0x100
	v_mov_b32_e32 v36, 0
	s_addc_u32 s55, s55, 0
	s_mov_b32 s6, 0
	s_waitcnt lgkmcnt(0)
	v_mov_b32_e32 v37, v36
	v_mov_b32_e32 v38, v36
	v_mov_b32_e32 v39, v36
	v_mov_b32_e32 v52, v36
	v_mov_b32_e32 v53, v36
	v_mov_b32_e32 v54, v36
	v_mov_b32_e32 v55, v36
	v_mov_b32_e32 v80, v36
	v_mov_b32_e32 v81, v36
	v_mov_b32_e32 v82, v36
	v_mov_b32_e32 v83, v36
	v_mov_b32_e32 v84, v36
	v_mov_b32_e32 v85, v36
	v_mov_b32_e32 v86, v36
	v_mov_b32_e32 v87, v36
	v_mov_b32_e32 v96, v36
	v_mov_b32_e32 v97, v36
	v_mov_b32_e32 v98, v36
	v_mov_b32_e32 v99, v36
	v_mov_b32_e32 v100, v36
	v_mov_b32_e32 v101, v36
	v_mov_b32_e32 v102, v36
	v_mov_b32_e32 v103, v36
	v_mov_b32_e32 v112, v36
	v_mov_b32_e32 v113, v36
	v_mov_b32_e32 v114, v36
	v_mov_b32_e32 v115, v36
	v_mov_b32_e32 v116, v36
	v_mov_b32_e32 v117, v36
	v_mov_b32_e32 v118, v36
	v_mov_b32_e32 v119, v36
	v_mov_b32_e32 v72, v36
	v_mov_b32_e32 v73, v36
	v_mov_b32_e32 v74, v36
	v_mov_b32_e32 v75, v36
	v_mov_b32_e32 v76, v36
	v_mov_b32_e32 v77, v36
	v_mov_b32_e32 v78, v36
	v_mov_b32_e32 v79, v36
	v_mov_b32_e32 v88, v36
	v_mov_b32_e32 v89, v36
	v_mov_b32_e32 v90, v36
	v_mov_b32_e32 v91, v36
	v_mov_b32_e32 v92, v36
	v_mov_b32_e32 v93, v36
	v_mov_b32_e32 v94, v36
	v_mov_b32_e32 v95, v36
	v_mov_b32_e32 v104, v36
	v_mov_b32_e32 v105, v36
	v_mov_b32_e32 v106, v36
	v_mov_b32_e32 v107, v36
	v_mov_b32_e32 v108, v36
	v_mov_b32_e32 v109, v36
	v_mov_b32_e32 v110, v36
	v_mov_b32_e32 v111, v36
	v_mov_b32_e32 v120, v36
	v_mov_b32_e32 v121, v36
	v_mov_b32_e32 v122, v36
	v_mov_b32_e32 v123, v36
	v_mov_b32_e32 v124, v36
	v_mov_b32_e32 v125, v36
	v_mov_b32_e32 v126, v36
	v_mov_b32_e32 v127, v36
	v_mov_b32_e32 v0, v36
	v_mov_b32_e32 v1, v36
	v_mov_b32_e32 v2, v36
	v_mov_b32_e32 v3, v36
	v_mov_b32_e32 v4, v36
	v_mov_b32_e32 v5, v36
	v_mov_b32_e32 v6, v36
	v_mov_b32_e32 v7, v36
	v_mov_b32_e32 v8, v36
	v_mov_b32_e32 v9, v36
	v_mov_b32_e32 v10, v36
	v_mov_b32_e32 v11, v36
	v_mov_b32_e32 v12, v36
	v_mov_b32_e32 v13, v36
	v_mov_b32_e32 v14, v36
	v_mov_b32_e32 v15, v36
	v_mov_b32_e32 v24, v36
	v_mov_b32_e32 v25, v36
	v_mov_b32_e32 v26, v36
	v_mov_b32_e32 v27, v36
	v_mov_b32_e32 v28, v36
	v_mov_b32_e32 v29, v36
	v_mov_b32_e32 v30, v36
	v_mov_b32_e32 v31, v36
	v_mov_b32_e32 v44, v36
	v_mov_b32_e32 v45, v36
	v_mov_b32_e32 v46, v36
	v_mov_b32_e32 v47, v36
	v_mov_b32_e32 v48, v36
	v_mov_b32_e32 v49, v36
	v_mov_b32_e32 v50, v36
	v_mov_b32_e32 v51, v36
	v_mov_b32_e32 v16, v36
	v_mov_b32_e32 v17, v36
	v_mov_b32_e32 v18, v36
	v_mov_b32_e32 v19, v36
	v_mov_b32_e32 v20, v36
	v_mov_b32_e32 v21, v36
	v_mov_b32_e32 v22, v36
	v_mov_b32_e32 v23, v36
	v_mov_b32_e32 v32, v36
	v_mov_b32_e32 v33, v36
	v_mov_b32_e32 v34, v36
	v_mov_b32_e32 v35, v36
	v_mov_b32_e32 v40, v36
	v_mov_b32_e32 v41, v36
	v_mov_b32_e32 v42, v36
	v_mov_b32_e32 v43, v36
	v_mov_b32_e32 v56, v36
	v_mov_b32_e32 v57, v36
	v_mov_b32_e32 v58, v36
	v_mov_b32_e32 v59, v36
	v_mov_b32_e32 v60, v36
	v_mov_b32_e32 v61, v36
	v_mov_b32_e32 v62, v36
	v_mov_b32_e32 v63, v36
	v_mov_b32_e32 v64, v36
	v_mov_b32_e32 v65, v36
	v_mov_b32_e32 v66, v36
	v_mov_b32_e32 v67, v36
	v_mov_b32_e32 v68, v36
	v_mov_b32_e32 v69, v36
	v_mov_b32_e32 v70, v36
	v_mov_b32_e32 v71, v36
	s_cmp_eq_u32 s58, 1
	s_cbranch_scc0 .Lprio_skip_1
	s_setprio 1
.Lprio_skip_1:
.LBB0_560:
	s_add_i32 s57, s6, 2
	s_add_u32 s30, s42, 0xfff80080
	s_addc_u32 s7, s43, -1
	s_add_i32 s75, 0, 0x10000
	s_cmp_eq_u32 s56, s6
	s_cselect_b32 s7, s10, s7
	s_cselect_b32 s6, s41, s30
	s_cselect_b32 s31, s45, s55
	s_cselect_b32 s30, s49, s54
	s_add_i32 s77, 0, 0x14000
	v_add_u32_e32 v146, s75, v164
	v_add_u32_e32 v166, s77, v164
	ds_read_b128 v[128:131], v146
	ds_read_b128 v[132:135], v146 offset:1024
	ds_read_b128 v[142:145], v146 offset:2048
	ds_read_b128 v[146:149], v146 offset:3072
	ds_read_b128 v[150:153], v166
	ds_read_b128 v[154:157], v166 offset:1024
	ds_read_b128 v[158:161], v166 offset:2048
	ds_read_b128 v[178:181], v166 offset:3072
	v_lshl_add_u64 v[166:167], s[42:43], 0, v[138:139]
	s_add_i32 m0, s23, 0xc000
	ds_read_b128 v[182:185], v165
	ds_read_b128 v[186:189], v165 offset:1024
	ds_read_b128 v[190:193], v165 offset:2048
	ds_read_b128 v[194:197], v165 offset:3072
	ds_read_b128 v[198:201], v165 offset:4096
	ds_read_b128 v[202:205], v165 offset:5120
	ds_read_b128 v[206:209], v165 offset:6144
	ds_read_b128 v[226:229], v165 offset:7168
	global_load_lds_dwordx4 v[166:167], off
	v_lshl_add_u64 v[166:167], s[42:43], 0, v[140:141]
	s_add_i32 m0, s23, 0xe000
	s_nop 0
	global_load_lds_dwordx4 v[166:167], off
	s_waitcnt vmcnt(8)
	s_waitcnt lgkmcnt(0)
	s_barrier
; #define PG8_STAGE(bufoff, gbase, voff) do { _Pragma("unroll") for (int _i = 0; _i < 2; ++_i) \
;         __builtin_amdgcn_global_load_lds((const unsigned*)((const char*)(gbase) + (voff)[_i]), (PG8_LAS unsigned*)(lds + (bufoff) + ldsw + _i * 8192), 16, 0, 0); } while (0)
; #define PG8_LDA(dst, b, h) do { _Pragma("unroll") for (int m = 0; m < 4; ++m) _Pragma("unroll") for (int k = 0; k < 2; ++k) dst[m][k] = *(const PG8_LAS bf16x8*)(lds + PG8_SA(b, h) + aoff + m * 2048 + k * 1024); } while (0)
; #define PG8_MMA(ai, bj, At, Bt) do { __builtin_amdgcn_s_setprio(1); _Pragma("unroll") for (int m = 0; m < 4; ++m) _Pragma("unroll") for (int n = 0; n < 2; ++n) _Pragma("unroll") for (int k = 0; k < 2; ++k) \
;         acc[ai][bj][m][n] = __builtin_amdgcn_mfma_f32_16x16x32_bf16(Bt[n][k], At[m][k], acc[ai][bj][m][n], 0, 0, 0); __builtin_amdgcn_s_setprio(0); } while (0)
; #define PG8_WAIT_V(n) asm volatile("s_waitcnt vmcnt(" #n ")" ::: "memory")
; #define PG8_WAIT_L(n) asm volatile("s_waitcnt lgkmcnt(" #n ")" ::: "memory")
; #define PG8_BAR __builtin_amdgcn_s_barrier()
; #define PG8_SCHED __builtin_amdgcn_sched_barrier(0)
; template <class Epi, class Sched, bool ALIGN_EPI = false, bool SP2 = false>
; __device__ __forceinline__ void gemm_phase(PG8_LAS unsigned char* lds, const Gemm g, const Sched& S, const Epi& E) {
;     ...
;             PG8_WAIT_V(8); PG8_WAIT_L(0); PG8_BAR; PG8_MMA(0, 0, At, B0); PG8_MMA(0, 1, At, B1); PG8_BAR; PG8_SCHED;
;             PG8_LDA(At, 0, 1); PG8_STAGE(PG8_SB(0, 0), b2, voffB); PG8_STAGE(PG8_SB(0, 1), b2 + hstep, voffB); PG8_STAGE(PG8_SA(0, 0), a2, voffA);
;             PG8_WAIT_V(8); PG8_WAIT_L(0); PG8_BAR; PG8_MMA(1, 0, At, B0); PG8_MMA(1, 1, At, B1); PG8_BAR; PG8_SCHED;
	s_waitcnt lgkmcnt(0)
	v_mfma_f32_16x16x32_bf16 v[68:71], v[128:131], v[182:185], v[68:71]
	v_mfma_f32_16x16x32_bf16 v[64:67], v[142:145], v[182:185], v[64:67]
	v_mfma_f32_16x16x32_bf16 v[60:63], v[128:131], v[190:193], v[60:63]
	v_mfma_f32_16x16x32_bf16 v[56:59], v[142:145], v[190:193], v[56:59]
	v_mfma_f32_16x16x32_bf16 v[40:43], v[128:131], v[198:201], v[40:43]
	v_mfma_f32_16x16x32_bf16 v[32:35], v[142:145], v[198:201], v[32:35]
	v_mfma_f32_16x16x32_bf16 v[20:23], v[128:131], v[206:209], v[20:23]
	v_mfma_f32_16x16x32_bf16 v[16:19], v[142:145], v[206:209], v[16:19]
	v_mfma_f32_16x16x32_bf16 v[68:71], v[132:135], v[186:189], v[68:71]
	v_mfma_f32_16x16x32_bf16 v[64:67], v[146:149], v[186:189], v[64:67]
	v_mfma_f32_16x16x32_bf16 v[60:63], v[132:135], v[194:197], v[60:63]
	v_mfma_f32_16x16x32_bf16 v[56:59], v[146:149], v[194:197], v[56:59]
	v_mfma_f32_16x16x32_bf16 v[40:43], v[132:135], v[202:205], v[40:43]
	v_mfma_f32_16x16x32_bf16 v[32:35], v[146:149], v[202:205], v[32:35]
	v_mfma_f32_16x16x32_bf16 v[20:23], v[132:135], v[226:229], v[20:23]
	v_mfma_f32_16x16x32_bf16 v[16:19], v[146:149], v[226:229], v[16:19]
	v_mfma_f32_16x16x32_bf16 v[48:51], v[150:153], v[182:185], v[48:51]
	v_mfma_f32_16x16x32_bf16 v[44:47], v[158:161], v[182:185], v[44:47]
	v_mfma_f32_16x16x32_bf16 v[28:31], v[150:153], v[190:193], v[28:31]
	v_mfma_f32_16x16x32_bf16 v[24:27], v[158:161], v[190:193], v[24:27]
	v_mfma_f32_16x16x32_bf16 v[12:15], v[150:153], v[198:201], v[12:15]
	v_mfma_f32_16x16x32_bf16 v[8:11], v[158:161], v[198:201], v[8:11]
	v_mfma_f32_16x16x32_bf16 v[4:7], v[150:153], v[206:209], v[4:7]
	v_mfma_f32_16x16x32_bf16 v[0:3], v[158:161], v[206:209], v[0:3]
	v_mfma_f32_16x16x32_bf16 v[48:51], v[154:157], v[186:189], v[48:51]
	v_mfma_f32_16x16x32_bf16 v[44:47], v[178:181], v[186:189], v[44:47]
	v_mfma_f32_16x16x32_bf16 v[28:31], v[154:157], v[194:197], v[28:31]
	v_mfma_f32_16x16x32_bf16 v[24:27], v[178:181], v[194:197], v[24:27]
	v_mfma_f32_16x16x32_bf16 v[12:15], v[154:157], v[202:205], v[12:15]
	v_mfma_f32_16x16x32_bf16 v[8:11], v[178:181], v[202:205], v[8:11]
	v_mfma_f32_16x16x32_bf16 v[4:7], v[154:157], v[226:229], v[4:7]
	v_mfma_f32_16x16x32_bf16 v[0:3], v[178:181], v[226:229], v[0:3]
	s_barrier
	s_add_i32 s75, s75, s59
	v_lshl_add_u64 v[166:167], s[30:31], 0, v[168:169]
	s_mov_b32 m0, s75
	ds_read_b128 v[182:185], v165 offset:16384
	ds_read_b128 v[186:189], v165 offset:17408
	ds_read_b128 v[190:193], v165 offset:18432
	ds_read_b128 v[194:197], v165 offset:19456
	ds_read_b128 v[198:201], v165 offset:20480
	ds_read_b128 v[202:205], v165 offset:21504
	ds_read_b128 v[206:209], v165 offset:22528
	ds_read_b128 v[226:229], v165 offset:23552
	global_load_lds_dwordx4 v[166:167], off
	s_add_i32 m0, s75, 0x2000
	s_add_u32 s78, s30, 0x80000
	v_lshl_add_u64 v[230:231], s[30:31], 0, v[136:137]
	s_addc_u32 s79, s31, 0
	s_add_i32 s75, s77, s59
	global_load_lds_dwordx4 v[230:231], off
	v_lshl_add_u64 v[232:233], s[78:79], 0, v[168:169]
	s_mov_b32 m0, s75
	v_lshl_add_u64 v[234:235], s[6:7], 0, v[136:137]
	global_load_lds_dwordx4 v[232:233], off
	v_lshl_add_u64 v[232:233], s[78:79], 0, v[136:137]
	s_add_i32 m0, s75, 0x2000
	s_nop 0
	global_load_lds_dwordx4 v[232:233], off
	v_lshl_add_u64 v[232:233], s[6:7], 0, v[168:169]
	s_mov_b32 m0, s23
	s_nop 0
	global_load_lds_dwordx4 v[232:233], off
	s_mov_b32 m0, s64
	s_nop 0
	global_load_lds_dwordx4 v[234:235], off
	s_waitcnt vmcnt(8)
	s_waitcnt lgkmcnt(0)
	s_barrier
	s_waitcnt lgkmcnt(0)
	v_mfma_f32_16x16x32_bf16 v[124:127], v[128:131], v[182:185], v[124:127]
	v_mfma_f32_16x16x32_bf16 v[120:123], v[142:145], v[182:185], v[120:123]
	v_mfma_f32_16x16x32_bf16 v[108:111], v[128:131], v[190:193], v[108:111]
	v_mfma_f32_16x16x32_bf16 v[104:107], v[142:145], v[190:193], v[104:107]
	v_mfma_f32_16x16x32_bf16 v[92:95], v[128:131], v[198:201], v[92:95]
	v_mfma_f32_16x16x32_bf16 v[88:91], v[142:145], v[198:201], v[88:91]
	v_mfma_f32_16x16x32_bf16 v[76:79], v[128:131], v[206:209], v[76:79]
	v_mfma_f32_16x16x32_bf16 v[72:75], v[142:145], v[206:209], v[72:75]
	v_mfma_f32_16x16x32_bf16 v[124:127], v[132:135], v[186:189], v[124:127]
	v_mfma_f32_16x16x32_bf16 v[120:123], v[146:149], v[186:189], v[120:123]
	v_mfma_f32_16x16x32_bf16 v[108:111], v[132:135], v[194:197], v[108:111]
	v_mfma_f32_16x16x32_bf16 v[104:107], v[146:149], v[194:197], v[104:107]
	v_mfma_f32_16x16x32_bf16 v[92:95], v[132:135], v[202:205], v[92:95]
	v_mfma_f32_16x16x32_bf16 v[88:91], v[146:149], v[202:205], v[88:91]
	v_mfma_f32_16x16x32_bf16 v[76:79], v[132:135], v[226:229], v[76:79]
	v_mfma_f32_16x16x32_bf16 v[72:75], v[146:149], v[226:229], v[72:75]
	v_mfma_f32_16x16x32_bf16 v[116:119], v[150:153], v[182:185], v[116:119]
	v_mfma_f32_16x16x32_bf16 v[112:115], v[158:161], v[182:185], v[112:115]
	v_mfma_f32_16x16x32_bf16 v[100:103], v[150:153], v[190:193], v[100:103]
	v_mfma_f32_16x16x32_bf16 v[96:99], v[158:161], v[190:193], v[96:99]
	v_mfma_f32_16x16x32_bf16 v[84:87], v[150:153], v[198:201], v[84:87]
	v_mfma_f32_16x16x32_bf16 v[80:83], v[158:161], v[198:201], v[80:83]
	v_mfma_f32_16x16x32_bf16 v[52:55], v[150:153], v[206:209], v[52:55]
	v_mfma_f32_16x16x32_bf16 v[36:39], v[158:161], v[206:209], v[36:39]
	v_mfma_f32_16x16x32_bf16 v[116:119], v[154:157], v[186:189], v[116:119]
	v_mfma_f32_16x16x32_bf16 v[112:115], v[178:181], v[186:189], v[112:115]
	v_mfma_f32_16x16x32_bf16 v[100:103], v[154:157], v[194:197], v[100:103]
	v_mfma_f32_16x16x32_bf16 v[96:99], v[178:181], v[194:197], v[96:99]
	v_mfma_f32_16x16x32_bf16 v[84:87], v[154:157], v[202:205], v[84:87]
	v_mfma_f32_16x16x32_bf16 v[80:83], v[178:181], v[202:205], v[80:83]
	v_mfma_f32_16x16x32_bf16 v[52:55], v[154:157], v[226:229], v[52:55]
	v_mfma_f32_16x16x32_bf16 v[36:39], v[178:181], v[226:229], v[36:39]
	s_barrier
; #define PG8_STAGE(bufoff, gbase, voff) do { _Pragma("unroll") for (int _i = 0; _i < 2; ++_i) \
;         __builtin_amdgcn_global_load_lds((const unsigned*)((const char*)(gbase) + (voff)[_i]), (PG8_LAS unsigned*)(lds + (bufoff) + ldsw + _i * 8192), 16, 0, 0); } while (0)
; #define PG8_LDA(dst, b, h) do { _Pragma("unroll") for (int m = 0; m < 4; ++m) _Pragma("unroll") for (int k = 0; k < 2; ++k) dst[m][k] = *(const PG8_LAS bf16x8*)(lds + PG8_SA(b, h) + aoff + m * 2048 + k * 1024); } while (0)
; #define PG8_LDB(dst, b, h) do { _Pragma("unroll") for (int n = 0; n < 2; ++n) _Pragma("unroll") for (int k = 0; k < 2; ++k) dst[n][k] = *(const PG8_LAS bf16x8*)(lds + PG8_SB(b, h) + boff + n * 2048 + k * 1024); } while (0)
; #define PG8_MMA(ai, bj, At, Bt) do { __builtin_amdgcn_s_setprio(1); _Pragma("unroll") for (int m = 0; m < 4; ++m) _Pragma("unroll") for (int n = 0; n < 2; ++n) _Pragma("unroll") for (int k = 0; k < 2; ++k) \
;         acc[ai][bj][m][n] = __builtin_amdgcn_mfma_f32_16x16x32_bf16(Bt[n][k], At[m][k], acc[ai][bj][m][n], 0, 0, 0); __builtin_amdgcn_s_setprio(0); } while (0)
; #define PG8_WAIT_V(n) asm volatile("s_waitcnt vmcnt(" #n ")" ::: "memory")
; #define PG8_WAIT_L(n) asm volatile("s_waitcnt lgkmcnt(" #n ")" ::: "memory")
; #define PG8_BAR __builtin_amdgcn_s_barrier()
; #define PG8_SCHED __builtin_amdgcn_sched_barrier(0)
; template <class Epi, class Sched, bool ALIGN_EPI = false, bool SP2 = false>
; __device__ __forceinline__ void gemm_phase(PG8_LAS unsigned char* lds, const Gemm g, const Sched& S, const Epi& E) {
;     ...
;             PG8_LDB(B0, 1, 0); PG8_LDB(B1, 1, 1); PG8_SCHED; PG8_LDA(At, 1, 0); PG8_STAGE(PG8_SA(0, 1), a2 + hstep, voffA);
;             PG8_WAIT_V(8); PG8_WAIT_L(0); PG8_BAR; PG8_MMA(0, 0, At, B0); PG8_MMA(0, 1, At, B1); PG8_BAR; PG8_SCHED;
	s_add_i32 s75, 0, 0x18000
	s_add_i32 s77, 0, 0x1c000
	v_add_u32_e32 v146, s75, v164
	v_add_u32_e32 v178, s77, v164
	ds_read_b128 v[128:131], v146
	ds_read_b128 v[132:135], v146 offset:1024
	ds_read_b128 v[142:145], v146 offset:2048
	ds_read_b128 v[146:149], v146 offset:3072
	ds_read_b128 v[150:153], v178
	ds_read_b128 v[154:157], v178 offset:1024
	ds_read_b128 v[158:161], v178 offset:2048
	ds_read_b128 v[178:181], v178 offset:3072
	s_add_u32 s6, s6, 0x80000
	s_addc_u32 s7, s7, 0
	s_mov_b32 m0, s65
	v_lshl_add_u64 v[236:237], s[6:7], 0, v[168:169]
	ds_read_b128 v[182:185], v165 offset:32768
	ds_read_b128 v[186:189], v165 offset:33792
	ds_read_b128 v[190:193], v165 offset:34816
	ds_read_b128 v[194:197], v165 offset:35840
	ds_read_b128 v[198:201], v165 offset:36864
	ds_read_b128 v[202:205], v165 offset:37888
	ds_read_b128 v[206:209], v165 offset:38912
	ds_read_b128 v[226:229], v165 offset:39936
	global_load_lds_dwordx4 v[236:237], off
	v_lshl_add_u64 v[236:237], s[6:7], 0, v[136:137]
	s_mov_b32 m0, s66
	s_nop 0
	global_load_lds_dwordx4 v[236:237], off
	s_waitcnt vmcnt(8)
	s_waitcnt lgkmcnt(0)
	s_barrier
	s_waitcnt lgkmcnt(0)
	v_mfma_f32_16x16x32_bf16 v[68:71], v[128:131], v[182:185], v[68:71]
	v_mfma_f32_16x16x32_bf16 v[64:67], v[142:145], v[182:185], v[64:67]
	v_mfma_f32_16x16x32_bf16 v[60:63], v[128:131], v[190:193], v[60:63]
	v_mfma_f32_16x16x32_bf16 v[56:59], v[142:145], v[190:193], v[56:59]
	v_mfma_f32_16x16x32_bf16 v[40:43], v[128:131], v[198:201], v[40:43]
	v_mfma_f32_16x16x32_bf16 v[32:35], v[142:145], v[198:201], v[32:35]
	v_mfma_f32_16x16x32_bf16 v[20:23], v[128:131], v[206:209], v[20:23]
	v_mfma_f32_16x16x32_bf16 v[16:19], v[142:145], v[206:209], v[16:19]
	v_mfma_f32_16x16x32_bf16 v[68:71], v[132:135], v[186:189], v[68:71]
	v_mfma_f32_16x16x32_bf16 v[64:67], v[146:149], v[186:189], v[64:67]
	v_mfma_f32_16x16x32_bf16 v[60:63], v[132:135], v[194:197], v[60:63]
	v_mfma_f32_16x16x32_bf16 v[56:59], v[146:149], v[194:197], v[56:59]
	v_mfma_f32_16x16x32_bf16 v[40:43], v[132:135], v[202:205], v[40:43]
	v_mfma_f32_16x16x32_bf16 v[32:35], v[146:149], v[202:205], v[32:35]
	v_mfma_f32_16x16x32_bf16 v[20:23], v[132:135], v[226:229], v[20:23]
	v_mfma_f32_16x16x32_bf16 v[16:19], v[146:149], v[226:229], v[16:19]
	v_mfma_f32_16x16x32_bf16 v[48:51], v[150:153], v[182:185], v[48:51]
	v_mfma_f32_16x16x32_bf16 v[44:47], v[158:161], v[182:185], v[44:47]
	v_mfma_f32_16x16x32_bf16 v[28:31], v[150:153], v[190:193], v[28:31]
	v_mfma_f32_16x16x32_bf16 v[24:27], v[158:161], v[190:193], v[24:27]
	v_mfma_f32_16x16x32_bf16 v[12:15], v[150:153], v[198:201], v[12:15]
	v_mfma_f32_16x16x32_bf16 v[8:11], v[158:161], v[198:201], v[8:11]
	v_mfma_f32_16x16x32_bf16 v[4:7], v[150:153], v[206:209], v[4:7]
	v_mfma_f32_16x16x32_bf16 v[0:3], v[158:161], v[206:209], v[0:3]
	v_mfma_f32_16x16x32_bf16 v[48:51], v[154:157], v[186:189], v[48:51]
	v_mfma_f32_16x16x32_bf16 v[44:47], v[178:181], v[186:189], v[44:47]
	v_mfma_f32_16x16x32_bf16 v[28:31], v[154:157], v[194:197], v[28:31]
	v_mfma_f32_16x16x32_bf16 v[24:27], v[178:181], v[194:197], v[24:27]
	v_mfma_f32_16x16x32_bf16 v[12:15], v[154:157], v[202:205], v[12:15]
	v_mfma_f32_16x16x32_bf16 v[8:11], v[178:181], v[202:205], v[8:11]
	v_mfma_f32_16x16x32_bf16 v[4:7], v[154:157], v[226:229], v[4:7]
	v_mfma_f32_16x16x32_bf16 v[0:3], v[178:181], v[226:229], v[0:3]
	s_barrier
; #define PG8_STAGE(bufoff, gbase, voff) do { _Pragma("unroll") for (int _i = 0; _i < 2; ++_i) \
;         __builtin_amdgcn_global_load_lds((const unsigned*)((const char*)(gbase) + (voff)[_i]), (PG8_LAS unsigned*)(lds + (bufoff) + ldsw + _i * 8192), 16, 0, 0); } while (0)
; #define PG8_LDA(dst, b, h) do { _Pragma("unroll") for (int m = 0; m < 4; ++m) _Pragma("unroll") for (int k = 0; k < 2; ++k) dst[m][k] = *(const PG8_LAS bf16x8*)(lds + PG8_SA(b, h) + aoff + m * 2048 + k * 1024); } while (0)
; #define PG8_MMA(ai, bj, At, Bt) do { __builtin_amdgcn_s_setprio(1); _Pragma("unroll") for (int m = 0; m < 4; ++m) _Pragma("unroll") for (int n = 0; n < 2; ++n) _Pragma("unroll") for (int k = 0; k < 2; ++k) \
;         acc[ai][bj][m][n] = __builtin_amdgcn_mfma_f32_16x16x32_bf16(Bt[n][k], At[m][k], acc[ai][bj][m][n], 0, 0, 0); __builtin_amdgcn_s_setprio(0); } while (0)
; #define PG8_WAIT_V(n) asm volatile("s_waitcnt vmcnt(" #n ")" ::: "memory")
; #define PG8_WAIT_L(n) asm volatile("s_waitcnt lgkmcnt(" #n ")" ::: "memory")
; #define PG8_BAR __builtin_amdgcn_s_barrier()
; #define PG8_SCHED __builtin_amdgcn_sched_barrier(0)
; template <class Epi, class Sched, bool ALIGN_EPI = false, bool SP2 = false>
; __device__ __forceinline__ void gemm_phase(PG8_LAS unsigned char* lds, const Gemm g, const Sched& S, const Epi& E) {
;     ...
;         for (int t = 0; t < nt; t += 2) {
;     ...
;             PG8_LDA(At, 1, 1); PG8_STAGE(PG8_SB(1, 0), b3, voffB); PG8_STAGE(PG8_SB(1, 1), b3 + hstep, voffB); PG8_STAGE(PG8_SA(1, 0), a3, voffA);
;             PG8_WAIT_V(8); PG8_WAIT_L(0); PG8_BAR; PG8_MMA(1, 0, At, B0); PG8_MMA(1, 1, At, B1); PG8_BAR; PG8_SCHED;
	s_add_i32 s6, s75, s59
	v_lshl_add_u64 v[166:167], v[166:167], 0, s[20:21]
	s_mov_b32 m0, s6
	ds_read_b128 v[182:185], v165 offset:49152
	ds_read_b128 v[186:189], v165 offset:50176
	ds_read_b128 v[190:193], v165 offset:51200
	ds_read_b128 v[194:197], v165 offset:52224
	ds_read_b128 v[198:201], v165 offset:53248
	ds_read_b128 v[202:205], v165 offset:54272
	ds_read_b128 v[206:209], v165 offset:55296
	ds_read_b128 v[226:229], v165 offset:56320
	global_load_lds_dwordx4 v[166:167], off
	s_add_i32 m0, s6, 0x2000
	s_add_u32 s6, s30, 0x80080
	v_lshl_add_u64 v[166:167], v[230:231], 0, s[20:21]
	s_addc_u32 s7, s31, 0
	s_add_i32 s30, s77, s59
	global_load_lds_dwordx4 v[166:167], off
	v_lshl_add_u64 v[166:167], s[6:7], 0, v[168:169]
	s_mov_b32 m0, s30
	s_nop 0
	global_load_lds_dwordx4 v[166:167], off
	v_lshl_add_u64 v[166:167], s[6:7], 0, v[136:137]
	s_add_i32 m0, s30, 0x2000
	s_nop 0
	global_load_lds_dwordx4 v[166:167], off
	v_lshl_add_u64 v[166:167], v[232:233], 0, s[20:21]
	s_mov_b32 m0, s72
	s_nop 0
	global_load_lds_dwordx4 v[166:167], off
	v_lshl_add_u64 v[166:167], v[234:235], 0, s[20:21]
	s_mov_b32 m0, s73
	s_nop 0
	global_load_lds_dwordx4 v[166:167], off
	s_waitcnt vmcnt(8)
	s_waitcnt lgkmcnt(0)
	s_barrier
	s_waitcnt lgkmcnt(0)
	v_mfma_f32_16x16x32_bf16 v[124:127], v[128:131], v[182:185], v[124:127]
	v_mfma_f32_16x16x32_bf16 v[120:123], v[142:145], v[182:185], v[120:123]
	v_mfma_f32_16x16x32_bf16 v[108:111], v[128:131], v[190:193], v[108:111]
	v_mfma_f32_16x16x32_bf16 v[104:107], v[142:145], v[190:193], v[104:107]
	v_mfma_f32_16x16x32_bf16 v[92:95], v[128:131], v[198:201], v[92:95]
	v_mfma_f32_16x16x32_bf16 v[88:91], v[142:145], v[198:201], v[88:91]
	v_mfma_f32_16x16x32_bf16 v[76:79], v[128:131], v[206:209], v[76:79]
	v_mfma_f32_16x16x32_bf16 v[72:75], v[142:145], v[206:209], v[72:75]
	v_mfma_f32_16x16x32_bf16 v[124:127], v[132:135], v[186:189], v[124:127]
	v_mfma_f32_16x16x32_bf16 v[120:123], v[146:149], v[186:189], v[120:123]
	v_mfma_f32_16x16x32_bf16 v[108:111], v[132:135], v[194:197], v[108:111]
	v_mfma_f32_16x16x32_bf16 v[104:107], v[146:149], v[194:197], v[104:107]
	v_mfma_f32_16x16x32_bf16 v[92:95], v[132:135], v[202:205], v[92:95]
	v_mfma_f32_16x16x32_bf16 v[88:91], v[146:149], v[202:205], v[88:91]
	v_mfma_f32_16x16x32_bf16 v[76:79], v[132:135], v[226:229], v[76:79]
	v_mfma_f32_16x16x32_bf16 v[72:75], v[146:149], v[226:229], v[72:75]
	v_mfma_f32_16x16x32_bf16 v[116:119], v[150:153], v[182:185], v[116:119]
	v_mfma_f32_16x16x32_bf16 v[112:115], v[158:161], v[182:185], v[112:115]
	v_mfma_f32_16x16x32_bf16 v[100:103], v[150:153], v[190:193], v[100:103]
	v_mfma_f32_16x16x32_bf16 v[96:99], v[158:161], v[190:193], v[96:99]
	v_mfma_f32_16x16x32_bf16 v[84:87], v[150:153], v[198:201], v[84:87]
	v_mfma_f32_16x16x32_bf16 v[80:83], v[158:161], v[198:201], v[80:83]
	v_mfma_f32_16x16x32_bf16 v[52:55], v[150:153], v[206:209], v[52:55]
	v_mfma_f32_16x16x32_bf16 v[36:39], v[158:161], v[206:209], v[36:39]
	v_mfma_f32_16x16x32_bf16 v[116:119], v[154:157], v[186:189], v[116:119]
	v_mfma_f32_16x16x32_bf16 v[112:115], v[178:181], v[186:189], v[112:115]
	v_mfma_f32_16x16x32_bf16 v[100:103], v[154:157], v[194:197], v[100:103]
	v_mfma_f32_16x16x32_bf16 v[96:99], v[178:181], v[194:197], v[96:99]
	v_mfma_f32_16x16x32_bf16 v[84:87], v[154:157], v[202:205], v[84:87]
	v_mfma_f32_16x16x32_bf16 v[80:83], v[178:181], v[202:205], v[80:83]
	v_mfma_f32_16x16x32_bf16 v[52:55], v[154:157], v[226:229], v[52:55]
	v_mfma_f32_16x16x32_bf16 v[36:39], v[178:181], v[226:229], v[36:39]
	s_barrier
	s_add_u32 s42, s42, 0x100
	s_addc_u32 s43, s43, 0
	s_add_u32 s54, s54, 0x100
	s_addc_u32 s55, s55, 0
	s_cmp_ge_u32 s57, s5
	s_mov_b32 s6, s57
	s_cbranch_scc0 .LBB0_560
	s_setprio 0
	s_and_b64 vcc, exec, s[34:35]
	s_cbranch_vccz .LBB0_563
	s_barrier

; #define PG8_STAGE(bufoff, gbase, voff) do { _Pragma("unroll") for (int _i = 0; _i < 2; ++_i) \
;         __builtin_amdgcn_global_load_lds((const unsigned*)((const char*)(gbase) + (voff)[_i]), (PG8_LAS unsigned*)(lds + (bufoff) + ldsw + _i * 8192), 16, 0, 0); } while (0)
; #define PG8_LDA(dst, b, h) do { _Pragma("unroll") for (int m = 0; m < 4; ++m) _Pragma("unroll") for (int k = 0; k < 2; ++k) dst[m][k] = *(const PG8_LAS bf16x8*)(lds + PG8_SA(b, h) + aoff + m * 2048 + k * 1024); } while (0)
; #define PG8_LDB(dst, b, h) do { _Pragma("unroll") for (int n = 0; n < 2; ++n) _Pragma("unroll") for (int k = 0; k < 2; ++k) dst[n][k] = *(const PG8_LAS bf16x8*)(lds + PG8_SB(b, h) + boff + n * 2048 + k * 1024); } while (0)
; #define PG8_SCHED __builtin_amdgcn_sched_barrier(0)
; template <class Epi, class Sched, bool ALIGN_EPI = false, bool SP2 = false>
; __device__ __forceinline__ void gemm_phase(PG8_LAS unsigned char* lds, const Gemm g, const Sched& S, const Epi& E) {
;     ...
;         const bool has_next = S.next(ui + 1, nxt);
;         const char* nA = has_next ? (const char*)g.A + (size_t)nxt.pm * tstep + (size_t)nxt.k0 * kstep : cA; const char* nB = has_next ? (const char*)g.Bt + (size_t)nxt.pn * tstep + (size_t)nxt.k0 * kstep : cB;
;         const int nt = cur.nt;
;         for (int t = 0; t < nt; t += 2) {
;             const bool last = (t == nt - 2);
;             const char* a1 = cA + (size_t)(t + 1) * kstep;
;             const char* a2 = last ? nA : cA + (size_t)(t + 2) * kstep; const char* b2 = last ? nB : cB + (size_t)(t + 2) * kstep;
;             const char* a3 = a2 + kstep; const char* b3 = b2 + kstep;
;             if (last && has_next) S.a_ready(nxt);
;             if constexpr (SP2) {
;             PG8_LDB(B0, 0, 0); PG8_LDB(B1, 0, 1); PG8_SCHED; PG8_LDA(At, 0, 0); PG8_STAGE(PG8_SA(1, 1), a1 + hstep, voffA);
;     ...
;         for (int a = 0; a < 2; ++a)
; #pragma unroll
;             for (int b = 0; b < 2; ++b)
; #pragma unroll
;                 for (int m = 0; m < 4; ++m)
; #pragma unroll
;                     for (int n = 0; n < 2; ++n) acc[a][b][m][n] = (f32x4){0.f, 0.f, 0.f, 0.f};
.LBB0_785:
	s_ashr_i32 s87, s86, 31
	s_lshl_b64 s[2:3], s[86:87], 20
	s_add_u32 s28, s8, s2
	s_addc_u32 s29, s9, s3
	s_and_b64 s[2:3], s[58:59], exec
	s_cselect_b32 s10, s29, s51
	s_cselect_b32 s43, s28, s50
	s_ashr_i32 s25, s24, 31
	s_lshl_b64 s[2:3], s[24:25], 20
	s_add_u32 s2, s72, s2
	s_addc_u32 s3, s73, s3
	s_and_b64 s[6:7], s[58:59], exec
	s_cselect_b32 s25, s3, s49
	s_cselect_b32 s44, s2, s48
	s_add_u32 s40, s50, 0x80080
	s_addc_u32 s41, s51, 0
	s_add_u32 s45, s48, 0x100
	v_mov_b32_e32 v64, 0
	s_addc_u32 s46, s49, 0
	s_mov_b32 s47, -2
	v_mov_b32_e32 v65, v64
	v_mov_b32_e32 v66, v64
	v_mov_b32_e32 v67, v64
	v_mov_b32_e32 v100, v64
	v_mov_b32_e32 v101, v64
	v_mov_b32_e32 v102, v64
	v_mov_b32_e32 v103, v64
	v_mov_b32_e32 v72, v64
	v_mov_b32_e32 v73, v64
	v_mov_b32_e32 v74, v64
	v_mov_b32_e32 v75, v64
	v_mov_b32_e32 v112, v64
	v_mov_b32_e32 v113, v64
	v_mov_b32_e32 v114, v64
	v_mov_b32_e32 v115, v64
	v_mov_b32_e32 v80, v64
	v_mov_b32_e32 v81, v64
	v_mov_b32_e32 v82, v64
	v_mov_b32_e32 v83, v64
	v_mov_b32_e32 v120, v64
	v_mov_b32_e32 v121, v64
	v_mov_b32_e32 v122, v64
	v_mov_b32_e32 v123, v64
	v_mov_b32_e32 v88, v64
	v_mov_b32_e32 v89, v64
	v_mov_b32_e32 v90, v64
	v_mov_b32_e32 v91, v64
	v_mov_b32_e32 v128, v64
	v_mov_b32_e32 v129, v64
	v_mov_b32_e32 v130, v64
	v_mov_b32_e32 v131, v64
	v_mov_b32_e32 v68, v64
	v_mov_b32_e32 v69, v64
	v_mov_b32_e32 v70, v64
	v_mov_b32_e32 v71, v64
	v_mov_b32_e32 v108, v64
	v_mov_b32_e32 v109, v64
	v_mov_b32_e32 v110, v64
	v_mov_b32_e32 v111, v64
	v_mov_b32_e32 v76, v64
	v_mov_b32_e32 v77, v64
	v_mov_b32_e32 v78, v64
	v_mov_b32_e32 v79, v64
	v_mov_b32_e32 v116, v64
	v_mov_b32_e32 v117, v64
	v_mov_b32_e32 v118, v64
	v_mov_b32_e32 v119, v64
	v_mov_b32_e32 v84, v64
	v_mov_b32_e32 v85, v64
	v_mov_b32_e32 v86, v64
	v_mov_b32_e32 v87, v64
	v_mov_b32_e32 v124, v64
	v_mov_b32_e32 v125, v64
	v_mov_b32_e32 v126, v64
	v_mov_b32_e32 v127, v64
	v_mov_b32_e32 v92, v64
	v_mov_b32_e32 v93, v64
	v_mov_b32_e32 v94, v64
	v_mov_b32_e32 v95, v64
	v_mov_b32_e32 v132, v64
	v_mov_b32_e32 v133, v64
	v_mov_b32_e32 v134, v64
	v_mov_b32_e32 v135, v64
	v_mov_b32_e32 v0, v64
	v_mov_b32_e32 v1, v64
	v_mov_b32_e32 v2, v64
	v_mov_b32_e32 v3, v64
	v_mov_b32_e32 v32, v64
	v_mov_b32_e32 v33, v64
	v_mov_b32_e32 v34, v64
	v_mov_b32_e32 v35, v64
	v_mov_b32_e32 v8, v64
	v_mov_b32_e32 v9, v64
	v_mov_b32_e32 v10, v64
	v_mov_b32_e32 v11, v64
	v_mov_b32_e32 v40, v64
	v_mov_b32_e32 v41, v64
	v_mov_b32_e32 v42, v64
	v_mov_b32_e32 v43, v64
	v_mov_b32_e32 v16, v64
	v_mov_b32_e32 v17, v64
	v_mov_b32_e32 v18, v64
	v_mov_b32_e32 v19, v64
	v_mov_b32_e32 v48, v64
	v_mov_b32_e32 v49, v64
	v_mov_b32_e32 v50, v64
	v_mov_b32_e32 v51, v64
	v_mov_b32_e32 v24, v64
	v_mov_b32_e32 v25, v64
	v_mov_b32_e32 v26, v64
	v_mov_b32_e32 v27, v64
	v_mov_b32_e32 v56, v64
	v_mov_b32_e32 v57, v64
	v_mov_b32_e32 v58, v64
	v_mov_b32_e32 v59, v64
	v_mov_b32_e32 v4, v64
	v_mov_b32_e32 v5, v64
	v_mov_b32_e32 v6, v64
	v_mov_b32_e32 v7, v64
	v_mov_b32_e32 v36, v64
	v_mov_b32_e32 v37, v64
	v_mov_b32_e32 v38, v64
	v_mov_b32_e32 v39, v64
	v_mov_b32_e32 v12, v64
	v_mov_b32_e32 v13, v64
	v_mov_b32_e32 v14, v64
	v_mov_b32_e32 v15, v64
	v_mov_b32_e32 v44, v64
	v_mov_b32_e32 v45, v64
	v_mov_b32_e32 v46, v64
	v_mov_b32_e32 v47, v64
	v_mov_b32_e32 v20, v64
	v_mov_b32_e32 v21, v64
	v_mov_b32_e32 v22, v64
	v_mov_b32_e32 v23, v64
	v_mov_b32_e32 v52, v64
	v_mov_b32_e32 v53, v64
	v_mov_b32_e32 v54, v64
	v_mov_b32_e32 v55, v64
	v_mov_b32_e32 v28, v64
	v_mov_b32_e32 v29, v64
	v_mov_b32_e32 v30, v64
	v_mov_b32_e32 v31, v64
	v_mov_b32_e32 v60, v64
	v_mov_b32_e32 v61, v64
	v_mov_b32_e32 v62, v64
	v_mov_b32_e32 v63, v64
	s_cmp_eq_u32 s74, 1
	s_cbranch_scc0 .Lprio_skip_2
	s_setprio 1
.Lprio_skip_2:
.LBB0_786:
	s_add_u32 s6, s40, 0xfff80080
	s_addc_u32 s7, s41, -1
	s_add_i32 s48, 0, 0x10000
	s_cmp_eq_u32 s47, 28
	s_cselect_b32 s7, s10, s7
	s_cselect_b32 s6, s43, s6
	s_cselect_b32 s31, s25, s46
	s_cselect_b32 s30, s44, s45
	s_add_i32 s50, 0, 0x14000
	v_add_u32_e32 v140, s48, v227
	v_add_u32_e32 v156, s50, v227
	ds_read_b128 v[96:99], v140
	ds_read_b128 v[104:107], v140 offset:1024
	ds_read_b128 v[136:139], v140 offset:2048
	ds_read_b128 v[140:143], v140 offset:3072
	ds_read_b128 v[144:147], v156
	ds_read_b128 v[148:151], v156 offset:1024
	ds_read_b128 v[152:155], v156 offset:2048
	ds_read_b128 v[156:159], v156 offset:3072
	v_lshl_add_u64 v[230:231], s[40:41], 0, v[182:183]
	s_add_i32 m0, s77, 0xc000
	ds_read_b128 v[160:163], v228
	ds_read_b128 v[164:167], v228 offset:1024
	ds_read_b128 v[186:189], v228 offset:2048
	ds_read_b128 v[190:193], v228 offset:3072
	ds_read_b128 v[194:197], v228 offset:4096
	ds_read_b128 v[198:201], v228 offset:5120
	ds_read_b128 v[202:205], v228 offset:6144
	ds_read_b128 v[206:209], v228 offset:7168
	global_load_lds_dwordx4 v[230:231], off
	v_lshl_add_u64 v[230:231], s[40:41], 0, v[184:185]
	s_add_i32 m0, s77, 0xe000
	s_nop 0
	global_load_lds_dwordx4 v[230:231], off
	s_waitcnt vmcnt(8)
	s_waitcnt lgkmcnt(0)
	s_barrier
; #define PG8_STAGE(bufoff, gbase, voff) do { _Pragma("unroll") for (int _i = 0; _i < 2; ++_i) \
;         __builtin_amdgcn_global_load_lds((const unsigned*)((const char*)(gbase) + (voff)[_i]), (PG8_LAS unsigned*)(lds + (bufoff) + ldsw + _i * 8192), 16, 0, 0); } while (0)
; #define PG8_LDA(dst, b, h) do { _Pragma("unroll") for (int m = 0; m < 4; ++m) _Pragma("unroll") for (int k = 0; k < 2; ++k) dst[m][k] = *(const PG8_LAS bf16x8*)(lds + PG8_SA(b, h) + aoff + m * 2048 + k * 1024); } while (0)
; #define PG8_MMA(ai, bj, At, Bt) do { __builtin_amdgcn_s_setprio(1); _Pragma("unroll") for (int m = 0; m < 4; ++m) _Pragma("unroll") for (int n = 0; n < 2; ++n) _Pragma("unroll") for (int k = 0; k < 2; ++k) \
;         acc[ai][bj][m][n] = __builtin_amdgcn_mfma_f32_16x16x32_bf16(Bt[n][k], At[m][k], acc[ai][bj][m][n], 0, 0, 0); __builtin_amdgcn_s_setprio(0); } while (0)
; #define PG8_WAIT_V(n) asm volatile("s_waitcnt vmcnt(" #n ")" ::: "memory")
; #define PG8_WAIT_L(n) asm volatile("s_waitcnt lgkmcnt(" #n ")" ::: "memory")
; #define PG8_BAR __builtin_amdgcn_s_barrier()
; #define PG8_SCHED __builtin_amdgcn_sched_barrier(0)
; template <class Epi, class Sched, bool ALIGN_EPI = false, bool SP2 = false>
; __device__ __forceinline__ void gemm_phase(PG8_LAS unsigned char* lds, const Gemm g, const Sched& S, const Epi& E) {
;     ...
;             PG8_WAIT_V(8); PG8_WAIT_L(0); PG8_BAR; PG8_MMA(0, 0, At, B0); PG8_MMA(0, 1, At, B1); PG8_BAR; PG8_SCHED;
;             PG8_LDA(At, 0, 1); PG8_STAGE(PG8_SB(0, 0), b2, voffB); PG8_STAGE(PG8_SB(0, 1), b2 + hstep, voffB); PG8_STAGE(PG8_SA(0, 0), a2, voffA);
;             PG8_WAIT_V(8); PG8_WAIT_L(0); PG8_BAR; PG8_MMA(1, 0, At, B0); PG8_MMA(1, 1, At, B1); PG8_BAR; PG8_SCHED;
	s_waitcnt lgkmcnt(0)
	v_mfma_f32_16x16x32_bf16 v[60:63], v[96:99], v[160:163], v[60:63]
	v_mfma_f32_16x16x32_bf16 v[28:31], v[136:139], v[160:163], v[28:31]
	v_mfma_f32_16x16x32_bf16 v[52:55], v[96:99], v[186:189], v[52:55]
	v_mfma_f32_16x16x32_bf16 v[20:23], v[136:139], v[186:189], v[20:23]
	v_mfma_f32_16x16x32_bf16 v[44:47], v[96:99], v[194:197], v[44:47]
	v_mfma_f32_16x16x32_bf16 v[12:15], v[136:139], v[194:197], v[12:15]
	v_mfma_f32_16x16x32_bf16 v[36:39], v[96:99], v[202:205], v[36:39]
	v_mfma_f32_16x16x32_bf16 v[4:7], v[136:139], v[202:205], v[4:7]
	v_mfma_f32_16x16x32_bf16 v[60:63], v[104:107], v[164:167], v[60:63]
	v_mfma_f32_16x16x32_bf16 v[28:31], v[140:143], v[164:167], v[28:31]
	v_mfma_f32_16x16x32_bf16 v[52:55], v[104:107], v[190:193], v[52:55]
	v_mfma_f32_16x16x32_bf16 v[20:23], v[140:143], v[190:193], v[20:23]
	v_mfma_f32_16x16x32_bf16 v[44:47], v[104:107], v[198:201], v[44:47]
	v_mfma_f32_16x16x32_bf16 v[12:15], v[140:143], v[198:201], v[12:15]
	v_mfma_f32_16x16x32_bf16 v[36:39], v[104:107], v[206:209], v[36:39]
	v_mfma_f32_16x16x32_bf16 v[4:7], v[140:143], v[206:209], v[4:7]
	v_mfma_f32_16x16x32_bf16 v[56:59], v[144:147], v[160:163], v[56:59]
	v_mfma_f32_16x16x32_bf16 v[24:27], v[152:155], v[160:163], v[24:27]
	v_mfma_f32_16x16x32_bf16 v[48:51], v[144:147], v[186:189], v[48:51]
	v_mfma_f32_16x16x32_bf16 v[16:19], v[152:155], v[186:189], v[16:19]
	v_mfma_f32_16x16x32_bf16 v[40:43], v[144:147], v[194:197], v[40:43]
	v_mfma_f32_16x16x32_bf16 v[8:11], v[152:155], v[194:197], v[8:11]
	v_mfma_f32_16x16x32_bf16 v[32:35], v[144:147], v[202:205], v[32:35]
	v_mfma_f32_16x16x32_bf16 v[0:3], v[152:155], v[202:205], v[0:3]
	v_mfma_f32_16x16x32_bf16 v[56:59], v[148:151], v[164:167], v[56:59]
	v_mfma_f32_16x16x32_bf16 v[24:27], v[156:159], v[164:167], v[24:27]
	v_mfma_f32_16x16x32_bf16 v[48:51], v[148:151], v[190:193], v[48:51]
	v_mfma_f32_16x16x32_bf16 v[16:19], v[156:159], v[190:193], v[16:19]
	v_mfma_f32_16x16x32_bf16 v[40:43], v[148:151], v[198:201], v[40:43]
	v_mfma_f32_16x16x32_bf16 v[8:11], v[156:159], v[198:201], v[8:11]
	v_mfma_f32_16x16x32_bf16 v[32:35], v[148:151], v[206:209], v[32:35]
	v_mfma_f32_16x16x32_bf16 v[0:3], v[156:159], v[206:209], v[0:3]
	s_barrier
	s_add_i32 s48, s48, s75
	v_lshl_add_u64 v[230:231], s[30:31], 0, v[180:181]
	s_mov_b32 m0, s48
	ds_read_b128 v[160:163], v228 offset:16384
	ds_read_b128 v[164:167], v228 offset:17408
	ds_read_b128 v[186:189], v228 offset:18432
	ds_read_b128 v[190:193], v228 offset:19456
	ds_read_b128 v[194:197], v228 offset:20480
	ds_read_b128 v[198:201], v228 offset:21504
	ds_read_b128 v[202:205], v228 offset:22528
	ds_read_b128 v[206:209], v228 offset:23552
	global_load_lds_dwordx4 v[230:231], off
	s_add_i32 m0, s48, 0x2000
	s_add_u32 s48, s30, 0x80000
	v_lshl_add_u64 v[232:233], s[30:31], 0, v[178:179]
	s_addc_u32 s49, s31, 0
	s_add_i32 s50, s50, s75
	global_load_lds_dwordx4 v[232:233], off
	v_lshl_add_u64 v[234:235], s[48:49], 0, v[180:181]
	s_mov_b32 m0, s50
	v_lshl_add_u64 v[236:237], s[6:7], 0, v[178:179]
	global_load_lds_dwordx4 v[234:235], off
	v_lshl_add_u64 v[234:235], s[48:49], 0, v[178:179]
	s_add_i32 m0, s50, 0x2000
	s_nop 0
	global_load_lds_dwordx4 v[234:235], off
	v_lshl_add_u64 v[234:235], s[6:7], 0, v[180:181]
	s_mov_b32 m0, s77
	s_nop 0
	global_load_lds_dwordx4 v[234:235], off
	s_mov_b32 m0, s78
	s_nop 0
	global_load_lds_dwordx4 v[236:237], off
	s_waitcnt vmcnt(8)
	s_waitcnt lgkmcnt(0)
	s_barrier
	s_waitcnt lgkmcnt(0)
	v_mfma_f32_16x16x32_bf16 v[132:135], v[96:99], v[160:163], v[132:135]
	v_mfma_f32_16x16x32_bf16 v[92:95], v[136:139], v[160:163], v[92:95]
	v_mfma_f32_16x16x32_bf16 v[124:127], v[96:99], v[186:189], v[124:127]
	v_mfma_f32_16x16x32_bf16 v[84:87], v[136:139], v[186:189], v[84:87]
	v_mfma_f32_16x16x32_bf16 v[116:119], v[96:99], v[194:197], v[116:119]
	v_mfma_f32_16x16x32_bf16 v[76:79], v[136:139], v[194:197], v[76:79]
	v_mfma_f32_16x16x32_bf16 v[68:71], v[136:139], v[202:205], v[68:71]
	v_mfma_f32_16x16x32_bf16 v[132:135], v[104:107], v[164:167], v[132:135]
	v_mfma_f32_16x16x32_bf16 v[92:95], v[140:143], v[164:167], v[92:95]
	v_mfma_f32_16x16x32_bf16 v[124:127], v[104:107], v[190:193], v[124:127]
	v_mfma_f32_16x16x32_bf16 v[84:87], v[140:143], v[190:193], v[84:87]
	v_mfma_f32_16x16x32_bf16 v[116:119], v[104:107], v[198:201], v[116:119]
	v_mfma_f32_16x16x32_bf16 v[76:79], v[140:143], v[198:201], v[76:79]
	v_mfma_f32_16x16x32_bf16 v[96:99], v[96:99], v[202:205], v[108:111]
	v_mfma_f32_16x16x32_bf16 v[68:71], v[140:143], v[206:209], v[68:71]
	v_mfma_f32_16x16x32_bf16 v[96:99], v[104:107], v[206:209], v[96:99]
	v_mfma_f32_16x16x32_bf16 v[108:111], v[144:147], v[186:189], v[120:123]
	v_mfma_f32_16x16x32_bf16 v[88:91], v[152:155], v[160:163], v[88:91]
	v_mfma_f32_16x16x32_bf16 v[120:123], v[148:151], v[190:193], v[108:111]
	v_mfma_f32_16x16x32_bf16 v[80:83], v[152:155], v[186:189], v[80:83]
	v_mfma_f32_16x16x32_bf16 v[108:111], v[144:147], v[194:197], v[112:115]
	v_mfma_f32_16x16x32_bf16 v[72:75], v[152:155], v[194:197], v[72:75]
	v_mfma_f32_16x16x32_bf16 v[100:103], v[144:147], v[202:205], v[100:103]
	v_mfma_f32_16x16x32_bf16 v[64:67], v[152:155], v[202:205], v[64:67]
	v_mfma_f32_16x16x32_bf16 v[104:107], v[144:147], v[160:163], v[128:131]
	v_mfma_f32_16x16x32_bf16 v[88:91], v[156:159], v[164:167], v[88:91]
	v_mfma_f32_16x16x32_bf16 v[80:83], v[156:159], v[190:193], v[80:83]
	v_mfma_f32_16x16x32_bf16 v[112:115], v[148:151], v[198:201], v[108:111]
	v_mfma_f32_16x16x32_bf16 v[72:75], v[156:159], v[198:201], v[72:75]
	v_mfma_f32_16x16x32_bf16 v[100:103], v[148:151], v[206:209], v[100:103]
	v_mfma_f32_16x16x32_bf16 v[64:67], v[156:159], v[206:209], v[64:67]
	v_mfma_f32_16x16x32_bf16 v[104:107], v[148:151], v[164:167], v[104:107]
	s_barrier
; #define PG8_STAGE(bufoff, gbase, voff) do { _Pragma("unroll") for (int _i = 0; _i < 2; ++_i) \
;         __builtin_amdgcn_global_load_lds((const unsigned*)((const char*)(gbase) + (voff)[_i]), (PG8_LAS unsigned*)(lds + (bufoff) + ldsw + _i * 8192), 16, 0, 0); } while (0)
; #define PG8_LDA(dst, b, h) do { _Pragma("unroll") for (int m = 0; m < 4; ++m) _Pragma("unroll") for (int k = 0; k < 2; ++k) dst[m][k] = *(const PG8_LAS bf16x8*)(lds + PG8_SA(b, h) + aoff + m * 2048 + k * 1024); } while (0)
; #define PG8_LDB(dst, b, h) do { _Pragma("unroll") for (int n = 0; n < 2; ++n) _Pragma("unroll") for (int k = 0; k < 2; ++k) dst[n][k] = *(const PG8_LAS bf16x8*)(lds + PG8_SB(b, h) + boff + n * 2048 + k * 1024); } while (0)
; #define PG8_MMA(ai, bj, At, Bt) do { __builtin_amdgcn_s_setprio(1); _Pragma("unroll") for (int m = 0; m < 4; ++m) _Pragma("unroll") for (int n = 0; n < 2; ++n) _Pragma("unroll") for (int k = 0; k < 2; ++k) \
;         acc[ai][bj][m][n] = __builtin_amdgcn_mfma_f32_16x16x32_bf16(Bt[n][k], At[m][k], acc[ai][bj][m][n], 0, 0, 0); __builtin_amdgcn_s_setprio(0); } while (0)
; #define PG8_WAIT_V(n) asm volatile("s_waitcnt vmcnt(" #n ")" ::: "memory")
; #define PG8_WAIT_L(n) asm volatile("s_waitcnt lgkmcnt(" #n ")" ::: "memory")
; #define PG8_BAR __builtin_amdgcn_s_barrier()
; #define PG8_SCHED __builtin_amdgcn_sched_barrier(0)
; template <class Epi, class Sched, bool ALIGN_EPI = false, bool SP2 = false>
; __device__ __forceinline__ void gemm_phase(PG8_LAS unsigned char* lds, const Gemm g, const Sched& S, const Epi& E) {
;     ...
;             PG8_LDB(B0, 1, 0); PG8_LDB(B1, 1, 1); PG8_SCHED; PG8_LDA(At, 1, 0); PG8_STAGE(PG8_SA(0, 1), a2 + hstep, voffA);
;             PG8_WAIT_V(8); PG8_WAIT_L(0); PG8_BAR; PG8_MMA(0, 0, At, B0); PG8_MMA(0, 1, At, B1); PG8_BAR; PG8_SCHED;
	s_add_i32 s48, 0, 0x18000
	s_add_i32 s49, 0, 0x1c000
	v_add_u32_e32 v140, s48, v227
	v_add_u32_e32 v156, s49, v227
	ds_read_b128 v[108:111], v140
	ds_read_b128 v[128:131], v140 offset:1024
	ds_read_b128 v[136:139], v140 offset:2048
	ds_read_b128 v[140:143], v140 offset:3072
	ds_read_b128 v[144:147], v156
	ds_read_b128 v[148:151], v156 offset:1024
	ds_read_b128 v[152:155], v156 offset:2048
	ds_read_b128 v[156:159], v156 offset:3072
	s_add_u32 s6, s6, 0x80000
	s_addc_u32 s7, s7, 0
	s_mov_b32 m0, s79
	v_lshl_add_u64 v[238:239], s[6:7], 0, v[180:181]
	ds_read_b128 v[160:163], v228 offset:32768
	ds_read_b128 v[164:167], v228 offset:33792
	ds_read_b128 v[186:189], v228 offset:34816
	ds_read_b128 v[190:193], v228 offset:35840
	ds_read_b128 v[194:197], v228 offset:36864
	ds_read_b128 v[198:201], v228 offset:37888
	ds_read_b128 v[202:205], v228 offset:38912
	ds_read_b128 v[206:209], v228 offset:39936
	global_load_lds_dwordx4 v[238:239], off
	v_lshl_add_u64 v[238:239], s[6:7], 0, v[178:179]
	s_mov_b32 m0, s80
	s_nop 0
	global_load_lds_dwordx4 v[238:239], off
	s_waitcnt vmcnt(8)
	s_waitcnt lgkmcnt(0)
	s_barrier
	s_waitcnt lgkmcnt(0)
	v_mfma_f32_16x16x32_bf16 v[60:63], v[108:111], v[160:163], v[60:63]
	v_mfma_f32_16x16x32_bf16 v[28:31], v[136:139], v[160:163], v[28:31]
	v_mfma_f32_16x16x32_bf16 v[52:55], v[108:111], v[186:189], v[52:55]
	v_mfma_f32_16x16x32_bf16 v[20:23], v[136:139], v[186:189], v[20:23]
	v_mfma_f32_16x16x32_bf16 v[44:47], v[108:111], v[194:197], v[44:47]
	v_mfma_f32_16x16x32_bf16 v[12:15], v[136:139], v[194:197], v[12:15]
	v_mfma_f32_16x16x32_bf16 v[36:39], v[108:111], v[202:205], v[36:39]
	v_mfma_f32_16x16x32_bf16 v[4:7], v[136:139], v[202:205], v[4:7]
	v_mfma_f32_16x16x32_bf16 v[60:63], v[128:131], v[164:167], v[60:63]
	v_mfma_f32_16x16x32_bf16 v[28:31], v[140:143], v[164:167], v[28:31]
	v_mfma_f32_16x16x32_bf16 v[52:55], v[128:131], v[190:193], v[52:55]
	v_mfma_f32_16x16x32_bf16 v[20:23], v[140:143], v[190:193], v[20:23]
	v_mfma_f32_16x16x32_bf16 v[44:47], v[128:131], v[198:201], v[44:47]
	v_mfma_f32_16x16x32_bf16 v[12:15], v[140:143], v[198:201], v[12:15]
	v_mfma_f32_16x16x32_bf16 v[36:39], v[128:131], v[206:209], v[36:39]
	v_mfma_f32_16x16x32_bf16 v[4:7], v[140:143], v[206:209], v[4:7]
	v_mfma_f32_16x16x32_bf16 v[56:59], v[144:147], v[160:163], v[56:59]
	v_mfma_f32_16x16x32_bf16 v[24:27], v[152:155], v[160:163], v[24:27]
	v_mfma_f32_16x16x32_bf16 v[48:51], v[144:147], v[186:189], v[48:51]
	v_mfma_f32_16x16x32_bf16 v[16:19], v[152:155], v[186:189], v[16:19]
	v_mfma_f32_16x16x32_bf16 v[40:43], v[144:147], v[194:197], v[40:43]
	v_mfma_f32_16x16x32_bf16 v[8:11], v[152:155], v[194:197], v[8:11]
	v_mfma_f32_16x16x32_bf16 v[32:35], v[144:147], v[202:205], v[32:35]
	v_mfma_f32_16x16x32_bf16 v[0:3], v[152:155], v[202:205], v[0:3]
	v_mfma_f32_16x16x32_bf16 v[56:59], v[148:151], v[164:167], v[56:59]
	v_mfma_f32_16x16x32_bf16 v[24:27], v[156:159], v[164:167], v[24:27]
	v_mfma_f32_16x16x32_bf16 v[48:51], v[148:151], v[190:193], v[48:51]
	v_mfma_f32_16x16x32_bf16 v[16:19], v[156:159], v[190:193], v[16:19]
	v_mfma_f32_16x16x32_bf16 v[40:43], v[148:151], v[198:201], v[40:43]
	v_mfma_f32_16x16x32_bf16 v[8:11], v[156:159], v[198:201], v[8:11]
	v_mfma_f32_16x16x32_bf16 v[32:35], v[148:151], v[206:209], v[32:35]
	v_mfma_f32_16x16x32_bf16 v[0:3], v[156:159], v[206:209], v[0:3]
	s_barrier
; #define PG8_STAGE(bufoff, gbase, voff) do { _Pragma("unroll") for (int _i = 0; _i < 2; ++_i) \
;         __builtin_amdgcn_global_load_lds((const unsigned*)((const char*)(gbase) + (voff)[_i]), (PG8_LAS unsigned*)(lds + (bufoff) + ldsw + _i * 8192), 16, 0, 0); } while (0)
; #define PG8_LDA(dst, b, h) do { _Pragma("unroll") for (int m = 0; m < 4; ++m) _Pragma("unroll") for (int k = 0; k < 2; ++k) dst[m][k] = *(const PG8_LAS bf16x8*)(lds + PG8_SA(b, h) + aoff + m * 2048 + k * 1024); } while (0)
; #define PG8_MMA(ai, bj, At, Bt) do { __builtin_amdgcn_s_setprio(1); _Pragma("unroll") for (int m = 0; m < 4; ++m) _Pragma("unroll") for (int n = 0; n < 2; ++n) _Pragma("unroll") for (int k = 0; k < 2; ++k) \
;         acc[ai][bj][m][n] = __builtin_amdgcn_mfma_f32_16x16x32_bf16(Bt[n][k], At[m][k], acc[ai][bj][m][n], 0, 0, 0); __builtin_amdgcn_s_setprio(0); } while (0)
; #define PG8_WAIT_V(n) asm volatile("s_waitcnt vmcnt(" #n ")" ::: "memory")
; #define PG8_WAIT_L(n) asm volatile("s_waitcnt lgkmcnt(" #n ")" ::: "memory")
; #define PG8_BAR __builtin_amdgcn_s_barrier()
; #define PG8_SCHED __builtin_amdgcn_sched_barrier(0)
; template <class Epi, class Sched, bool ALIGN_EPI = false, bool SP2 = false>
; __device__ __forceinline__ void gemm_phase(PG8_LAS unsigned char* lds, const Gemm g, const Sched& S, const Epi& E) {
;     ...
;         for (int t = 0; t < nt; t += 2) {
;     ...
;             PG8_LDA(At, 1, 1); PG8_STAGE(PG8_SB(1, 0), b3, voffB); PG8_STAGE(PG8_SB(1, 1), b3 + hstep, voffB); PG8_STAGE(PG8_SA(1, 0), a3, voffA);
;             PG8_WAIT_V(8); PG8_WAIT_L(0); PG8_BAR; PG8_MMA(1, 0, At, B0); PG8_MMA(1, 1, At, B1); PG8_BAR; PG8_SCHED;
	s_add_i32 s6, s48, s75
	v_lshl_add_u64 v[230:231], v[230:231], 0, s[20:21]
	s_mov_b32 m0, s6
	ds_read_b128 v[160:163], v228 offset:49152
	ds_read_b128 v[164:167], v228 offset:50176
	ds_read_b128 v[186:189], v228 offset:51200
	ds_read_b128 v[190:193], v228 offset:52224
	ds_read_b128 v[194:197], v228 offset:53248
	ds_read_b128 v[198:201], v228 offset:54272
	ds_read_b128 v[202:205], v228 offset:55296
	ds_read_b128 v[206:209], v228 offset:56320
	global_load_lds_dwordx4 v[230:231], off
	s_add_i32 m0, s6, 0x2000
	s_add_u32 s6, s30, 0x80080
	v_lshl_add_u64 v[230:231], v[232:233], 0, s[20:21]
	s_addc_u32 s7, s31, 0
	s_add_i32 s30, s49, s75
	global_load_lds_dwordx4 v[230:231], off
	v_lshl_add_u64 v[230:231], s[6:7], 0, v[180:181]
	s_mov_b32 m0, s30
	s_nop 0
	global_load_lds_dwordx4 v[230:231], off
	v_lshl_add_u64 v[230:231], s[6:7], 0, v[178:179]
	s_add_i32 m0, s30, 0x2000
	s_nop 0
	global_load_lds_dwordx4 v[230:231], off
	v_lshl_add_u64 v[230:231], v[234:235], 0, s[20:21]
	s_mov_b32 m0, s82
	s_nop 0
	global_load_lds_dwordx4 v[230:231], off
	v_lshl_add_u64 v[230:231], v[236:237], 0, s[20:21]
	s_mov_b32 m0, s83
	s_nop 0
	global_load_lds_dwordx4 v[230:231], off
	s_waitcnt vmcnt(8)
	s_waitcnt lgkmcnt(0)
	s_barrier
	s_waitcnt lgkmcnt(0)
	v_mfma_f32_16x16x32_bf16 v[132:135], v[108:111], v[160:163], v[132:135]
	v_mfma_f32_16x16x32_bf16 v[92:95], v[136:139], v[160:163], v[92:95]
	v_mfma_f32_16x16x32_bf16 v[124:127], v[108:111], v[186:189], v[124:127]
	v_mfma_f32_16x16x32_bf16 v[84:87], v[136:139], v[186:189], v[84:87]
	v_mfma_f32_16x16x32_bf16 v[116:119], v[108:111], v[194:197], v[116:119]
	v_mfma_f32_16x16x32_bf16 v[76:79], v[136:139], v[194:197], v[76:79]
	v_mfma_f32_16x16x32_bf16 v[96:99], v[108:111], v[202:205], v[96:99]
	v_mfma_f32_16x16x32_bf16 v[68:71], v[136:139], v[202:205], v[68:71]
	v_mfma_f32_16x16x32_bf16 v[132:135], v[128:131], v[164:167], v[132:135]
	v_mfma_f32_16x16x32_bf16 v[92:95], v[140:143], v[164:167], v[92:95]
	v_mfma_f32_16x16x32_bf16 v[124:127], v[128:131], v[190:193], v[124:127]
	v_mfma_f32_16x16x32_bf16 v[84:87], v[140:143], v[190:193], v[84:87]
	v_mfma_f32_16x16x32_bf16 v[116:119], v[128:131], v[198:201], v[116:119]
	v_mfma_f32_16x16x32_bf16 v[76:79], v[140:143], v[198:201], v[76:79]
	v_mfma_f32_16x16x32_bf16 v[108:111], v[128:131], v[206:209], v[96:99]
	v_mfma_f32_16x16x32_bf16 v[68:71], v[140:143], v[206:209], v[68:71]
	v_mfma_f32_16x16x32_bf16 v[96:99], v[144:147], v[160:163], v[104:107]
	v_mfma_f32_16x16x32_bf16 v[128:131], v[148:151], v[164:167], v[96:99]
	v_mfma_f32_16x16x32_bf16 v[96:99], v[144:147], v[186:189], v[120:123]
	v_mfma_f32_16x16x32_bf16 v[120:123], v[148:151], v[190:193], v[96:99]
	v_mfma_f32_16x16x32_bf16 v[96:99], v[144:147], v[194:197], v[112:115]
	v_mfma_f32_16x16x32_bf16 v[88:91], v[152:155], v[160:163], v[88:91]
	v_mfma_f32_16x16x32_bf16 v[80:83], v[152:155], v[186:189], v[80:83]
	v_mfma_f32_16x16x32_bf16 v[112:115], v[148:151], v[198:201], v[96:99]
	v_mfma_f32_16x16x32_bf16 v[72:75], v[152:155], v[194:197], v[72:75]
	v_mfma_f32_16x16x32_bf16 v[96:99], v[144:147], v[202:205], v[100:103]
	v_mfma_f32_16x16x32_bf16 v[64:67], v[152:155], v[202:205], v[64:67]
	v_mfma_f32_16x16x32_bf16 v[88:91], v[156:159], v[164:167], v[88:91]
	v_mfma_f32_16x16x32_bf16 v[80:83], v[156:159], v[190:193], v[80:83]
	v_mfma_f32_16x16x32_bf16 v[72:75], v[156:159], v[198:201], v[72:75]
	v_mfma_f32_16x16x32_bf16 v[100:103], v[148:151], v[206:209], v[96:99]
	v_mfma_f32_16x16x32_bf16 v[64:67], v[156:159], v[206:209], v[64:67]
	s_barrier
	s_add_i32 s47, s47, 2
	s_add_u32 s40, s40, 0x100
	s_addc_u32 s41, s41, 0
	s_add_u32 s45, s45, 0x100
	s_addc_u32 s46, s46, 0
	s_cmp_gt_u32 s47, 29
	s_cbranch_scc0 .LBB0_786
	s_setprio 0
	s_and_b64 vcc, exec, s[64:65]
	s_cbranch_vccz .LBB0_789
	s_barrier

; #define PG8_STAGE(bufoff, gbase, voff) do { _Pragma("unroll") for (int _i = 0; _i < 2; ++_i) \
;         __builtin_amdgcn_global_load_lds((const unsigned*)((const char*)(gbase) + (voff)[_i]), (PG8_LAS unsigned*)(lds + (bufoff) + ldsw + _i * 8192), 16, 0, 0); } while (0)
; #define PG8_LDA(dst, b, h) do { _Pragma("unroll") for (int m = 0; m < 4; ++m) _Pragma("unroll") for (int k = 0; k < 2; ++k) dst[m][k] = *(const PG8_LAS bf16x8*)(lds + PG8_SA(b, h) + aoff + m * 2048 + k * 1024); } while (0)
; #define PG8_LDB(dst, b, h) do { _Pragma("unroll") for (int n = 0; n < 2; ++n) _Pragma("unroll") for (int k = 0; k < 2; ++k) dst[n][k] = *(const PG8_LAS bf16x8*)(lds + PG8_SB(b, h) + boff + n * 2048 + k * 1024); } while (0)
; #define PG8_SCHED __builtin_amdgcn_sched_barrier(0)
; template <class Epi, class Sched, bool ALIGN_EPI = false, bool SP2 = false>
; __device__ __forceinline__ void gemm_phase(PG8_LAS unsigned char* lds, const Gemm g, const Sched& S, const Epi& E) {
;     ...
;         const bool has_next = S.next(ui + 1, nxt);
;         const char* nA = has_next ? (const char*)g.A + (size_t)nxt.pm * tstep + (size_t)nxt.k0 * kstep : cA; const char* nB = has_next ? (const char*)g.Bt + (size_t)nxt.pn * tstep + (size_t)nxt.k0 * kstep : cB;
;         const int nt = cur.nt;
;         for (int t = 0; t < nt; t += 2) {
;             const bool last = (t == nt - 2);
;             const char* a1 = cA + (size_t)(t + 1) * kstep;
;             const char* a2 = last ? nA : cA + (size_t)(t + 2) * kstep; const char* b2 = last ? nB : cB + (size_t)(t + 2) * kstep;
;             const char* a3 = a2 + kstep; const char* b3 = b2 + kstep;
;             if (last && has_next) S.a_ready(nxt);
;             if constexpr (SP2) {
;             PG8_LDB(B0, 0, 0); PG8_LDB(B1, 0, 1); PG8_SCHED; PG8_LDA(At, 0, 0); PG8_STAGE(PG8_SA(1, 1), a1 + hstep, voffA);
;     ...
;         for (int a = 0; a < 2; ++a)
; #pragma unroll
;             for (int b = 0; b < 2; ++b)
; #pragma unroll
;                 for (int m = 0; m < 4; ++m)
; #pragma unroll
;                     for (int n = 0; n < 2; ++n) acc[a][b][m][n] = (f32x4){0.f, 0.f, 0.f, 0.f};
.LBB0_916:
	s_add_i32 s8, s43, -2
	s_add_u32 s9, s34, 0x100
	v_mov_b32_e32 v56, 0
	s_addc_u32 s44, s35, 0
	s_mov_b32 s6, 0
	s_waitcnt lgkmcnt(0)
	v_mov_b32_e32 v57, v56
	v_mov_b32_e32 v58, v56
	v_mov_b32_e32 v59, v56
	v_mov_b32_e32 v68, v56
	v_mov_b32_e32 v69, v56
	v_mov_b32_e32 v70, v56
	v_mov_b32_e32 v71, v56
	v_mov_b32_e32 v80, v56
	v_mov_b32_e32 v81, v56
	v_mov_b32_e32 v82, v56
	v_mov_b32_e32 v83, v56
	v_mov_b32_e32 v84, v56
	v_mov_b32_e32 v85, v56
	v_mov_b32_e32 v86, v56
	v_mov_b32_e32 v87, v56
	v_mov_b32_e32 v96, v56
	v_mov_b32_e32 v97, v56
	v_mov_b32_e32 v98, v56
	v_mov_b32_e32 v99, v56
	v_mov_b32_e32 v100, v56
	v_mov_b32_e32 v101, v56
	v_mov_b32_e32 v102, v56
	v_mov_b32_e32 v103, v56
	v_mov_b32_e32 v112, v56
	v_mov_b32_e32 v113, v56
	v_mov_b32_e32 v114, v56
	v_mov_b32_e32 v115, v56
	v_mov_b32_e32 v116, v56
	v_mov_b32_e32 v117, v56
	v_mov_b32_e32 v118, v56
	v_mov_b32_e32 v119, v56
	v_mov_b32_e32 v72, v56
	v_mov_b32_e32 v73, v56
	v_mov_b32_e32 v74, v56
	v_mov_b32_e32 v75, v56
	v_mov_b32_e32 v76, v56
	v_mov_b32_e32 v77, v56
	v_mov_b32_e32 v78, v56
	v_mov_b32_e32 v79, v56
	v_mov_b32_e32 v88, v56
	v_mov_b32_e32 v89, v56
	v_mov_b32_e32 v90, v56
	v_mov_b32_e32 v91, v56
	v_mov_b32_e32 v92, v56
	v_mov_b32_e32 v93, v56
	v_mov_b32_e32 v94, v56
	v_mov_b32_e32 v95, v56
	v_mov_b32_e32 v104, v56
	v_mov_b32_e32 v105, v56
	v_mov_b32_e32 v106, v56
	v_mov_b32_e32 v107, v56
	v_mov_b32_e32 v108, v56
	v_mov_b32_e32 v109, v56
	v_mov_b32_e32 v110, v56
	v_mov_b32_e32 v111, v56
	v_mov_b32_e32 v120, v56
	v_mov_b32_e32 v121, v56
	v_mov_b32_e32 v122, v56
	v_mov_b32_e32 v123, v56
	v_mov_b32_e32 v124, v56
	v_mov_b32_e32 v125, v56
	v_mov_b32_e32 v126, v56
	v_mov_b32_e32 v127, v56
	v_mov_b32_e32 v0, v56
	v_mov_b32_e32 v1, v56
	v_mov_b32_e32 v2, v56
	v_mov_b32_e32 v3, v56
	v_mov_b32_e32 v4, v56
	v_mov_b32_e32 v5, v56
	v_mov_b32_e32 v6, v56
	v_mov_b32_e32 v7, v56
	v_mov_b32_e32 v8, v56
	v_mov_b32_e32 v9, v56
	v_mov_b32_e32 v10, v56
	v_mov_b32_e32 v11, v56
	v_mov_b32_e32 v12, v56
	v_mov_b32_e32 v13, v56
	v_mov_b32_e32 v14, v56
	v_mov_b32_e32 v15, v56
	v_mov_b32_e32 v24, v56
	v_mov_b32_e32 v25, v56
	v_mov_b32_e32 v26, v56
	v_mov_b32_e32 v27, v56
	v_mov_b32_e32 v28, v56
	v_mov_b32_e32 v29, v56
	v_mov_b32_e32 v30, v56
	v_mov_b32_e32 v31, v56
	v_mov_b32_e32 v40, v56
	v_mov_b32_e32 v41, v56
	v_mov_b32_e32 v42, v56
	v_mov_b32_e32 v43, v56
	v_mov_b32_e32 v44, v56
	v_mov_b32_e32 v45, v56
	v_mov_b32_e32 v46, v56
	v_mov_b32_e32 v47, v56
	v_mov_b32_e32 v16, v56
	v_mov_b32_e32 v17, v56
	v_mov_b32_e32 v18, v56
	v_mov_b32_e32 v19, v56
	v_mov_b32_e32 v20, v56
	v_mov_b32_e32 v21, v56
	v_mov_b32_e32 v22, v56
	v_mov_b32_e32 v23, v56
	v_mov_b32_e32 v32, v56
	v_mov_b32_e32 v33, v56
	v_mov_b32_e32 v34, v56
	v_mov_b32_e32 v35, v56
	v_mov_b32_e32 v36, v56
	v_mov_b32_e32 v37, v56
	v_mov_b32_e32 v38, v56
	v_mov_b32_e32 v39, v56
	v_mov_b32_e32 v48, v56
	v_mov_b32_e32 v49, v56
	v_mov_b32_e32 v50, v56
	v_mov_b32_e32 v51, v56
	v_mov_b32_e32 v52, v56
	v_mov_b32_e32 v53, v56
	v_mov_b32_e32 v54, v56
	v_mov_b32_e32 v55, v56
	v_mov_b32_e32 v60, v56
	v_mov_b32_e32 v61, v56
	v_mov_b32_e32 v62, v56
	v_mov_b32_e32 v63, v56
	v_mov_b32_e32 v64, v56
	v_mov_b32_e32 v65, v56
	v_mov_b32_e32 v66, v56
	v_mov_b32_e32 v67, v56
	s_cmp_eq_u32 s48, 1
	s_cbranch_scc0 .Lprio_skip_3
	s_setprio 1
.Lprio_skip_3:
.LBB0_917:
	s_add_i32 s45, s6, 2
	s_add_u32 s34, s28, 0x100
	s_addc_u32 s35, s29, 0
	s_add_i32 s65, 0, 0x10000
	s_cmp_eq_u32 s8, s6
	s_cselect_b32 s7, s25, s35
	s_cselect_b32 s6, s24, s34
	s_cselect_b32 s31, s27, s44
	s_cselect_b32 s30, s26, s9
	s_add_i32 s66, 0, 0x14000
	v_add_u32_e32 v146, s65, v160
	v_add_u32_e32 v166, s66, v160
	ds_read_b128 v[134:137], v146
	ds_read_b128 v[138:141], v146 offset:1024
	ds_read_b128 v[142:145], v146 offset:2048
	ds_read_b128 v[146:149], v146 offset:3072
	ds_read_b128 v[150:153], v166
	ds_read_b128 v[154:157], v166 offset:1024
	ds_read_b128 v[162:165], v166 offset:2048
	ds_read_b128 v[178:181], v166 offset:3072
	v_lshl_add_u64 v[166:167], s[28:29], 0, v[130:131]
	s_add_i32 m0, s50, 0xc000
	ds_read_b128 v[182:185], v161
	ds_read_b128 v[186:189], v161 offset:1024
	ds_read_b128 v[190:193], v161 offset:2048
	ds_read_b128 v[194:197], v161 offset:3072
	ds_read_b128 v[198:201], v161 offset:4096
	ds_read_b128 v[202:205], v161 offset:5120
	ds_read_b128 v[206:209], v161 offset:6144
	ds_read_b128 v[226:229], v161 offset:7168
	global_load_lds_dwordx4 v[166:167], off
	v_lshl_add_u64 v[166:167], s[28:29], 0, v[132:133]
	s_add_i32 m0, s50, 0xe000
	s_nop 0
	global_load_lds_dwordx4 v[166:167], off
	s_waitcnt vmcnt(8)
	s_waitcnt lgkmcnt(0)
	s_barrier
; #define PG8_STAGE(bufoff, gbase, voff) do { _Pragma("unroll") for (int _i = 0; _i < 2; ++_i) \
;         __builtin_amdgcn_global_load_lds((const unsigned*)((const char*)(gbase) + (voff)[_i]), (PG8_LAS unsigned*)(lds + (bufoff) + ldsw + _i * 8192), 16, 0, 0); } while (0)
; #define PG8_LDA(dst, b, h) do { _Pragma("unroll") for (int m = 0; m < 4; ++m) _Pragma("unroll") for (int k = 0; k < 2; ++k) dst[m][k] = *(const PG8_LAS bf16x8*)(lds + PG8_SA(b, h) + aoff + m * 2048 + k * 1024); } while (0)
; #define PG8_MMA(ai, bj, At, Bt) do { __builtin_amdgcn_s_setprio(1); _Pragma("unroll") for (int m = 0; m < 4; ++m) _Pragma("unroll") for (int n = 0; n < 2; ++n) _Pragma("unroll") for (int k = 0; k < 2; ++k) \
;         acc[ai][bj][m][n] = __builtin_amdgcn_mfma_f32_16x16x32_bf16(Bt[n][k], At[m][k], acc[ai][bj][m][n], 0, 0, 0); __builtin_amdgcn_s_setprio(0); } while (0)
; #define PG8_WAIT_V(n) asm volatile("s_waitcnt vmcnt(" #n ")" ::: "memory")
; #define PG8_WAIT_L(n) asm volatile("s_waitcnt lgkmcnt(" #n ")" ::: "memory")
; #define PG8_BAR __builtin_amdgcn_s_barrier()
; #define PG8_SCHED __builtin_amdgcn_sched_barrier(0)
; template <class Epi, class Sched, bool ALIGN_EPI = false, bool SP2 = false>
; __device__ __forceinline__ void gemm_phase(PG8_LAS unsigned char* lds, const Gemm g, const Sched& S, const Epi& E) {
;     ...
;             PG8_WAIT_V(8); PG8_WAIT_L(0); PG8_BAR; PG8_MMA(0, 0, At, B0); PG8_MMA(0, 1, At, B1); PG8_BAR; PG8_SCHED;
;             PG8_LDA(At, 0, 1); PG8_STAGE(PG8_SB(0, 0), b2, voffB); PG8_STAGE(PG8_SB(0, 1), b2 + hstep, voffB); PG8_STAGE(PG8_SA(0, 0), a2, voffA);
;             PG8_WAIT_V(8); PG8_WAIT_L(0); PG8_BAR; PG8_MMA(1, 0, At, B0); PG8_MMA(1, 1, At, B1); PG8_BAR; PG8_SCHED;
	s_waitcnt lgkmcnt(0)
	v_mfma_f32_16x16x32_bf16 v[64:67], v[134:137], v[182:185], v[64:67]
	v_mfma_f32_16x16x32_bf16 v[60:63], v[142:145], v[182:185], v[60:63]
	v_mfma_f32_16x16x32_bf16 v[52:55], v[134:137], v[190:193], v[52:55]
	v_mfma_f32_16x16x32_bf16 v[48:51], v[142:145], v[190:193], v[48:51]
	v_mfma_f32_16x16x32_bf16 v[36:39], v[134:137], v[198:201], v[36:39]
	v_mfma_f32_16x16x32_bf16 v[32:35], v[142:145], v[198:201], v[32:35]
	v_mfma_f32_16x16x32_bf16 v[20:23], v[134:137], v[206:209], v[20:23]
	v_mfma_f32_16x16x32_bf16 v[16:19], v[142:145], v[206:209], v[16:19]
	v_mfma_f32_16x16x32_bf16 v[64:67], v[138:141], v[186:189], v[64:67]
	v_mfma_f32_16x16x32_bf16 v[60:63], v[146:149], v[186:189], v[60:63]
	v_mfma_f32_16x16x32_bf16 v[52:55], v[138:141], v[194:197], v[52:55]
	v_mfma_f32_16x16x32_bf16 v[48:51], v[146:149], v[194:197], v[48:51]
	v_mfma_f32_16x16x32_bf16 v[36:39], v[138:141], v[202:205], v[36:39]
	v_mfma_f32_16x16x32_bf16 v[32:35], v[146:149], v[202:205], v[32:35]
	v_mfma_f32_16x16x32_bf16 v[20:23], v[138:141], v[226:229], v[20:23]
	v_mfma_f32_16x16x32_bf16 v[16:19], v[146:149], v[226:229], v[16:19]
	v_mfma_f32_16x16x32_bf16 v[44:47], v[150:153], v[182:185], v[44:47]
	v_mfma_f32_16x16x32_bf16 v[40:43], v[162:165], v[182:185], v[40:43]
	v_mfma_f32_16x16x32_bf16 v[28:31], v[150:153], v[190:193], v[28:31]
	v_mfma_f32_16x16x32_bf16 v[24:27], v[162:165], v[190:193], v[24:27]
	v_mfma_f32_16x16x32_bf16 v[12:15], v[150:153], v[198:201], v[12:15]
	v_mfma_f32_16x16x32_bf16 v[8:11], v[162:165], v[198:201], v[8:11]
	v_mfma_f32_16x16x32_bf16 v[4:7], v[150:153], v[206:209], v[4:7]
	v_mfma_f32_16x16x32_bf16 v[0:3], v[162:165], v[206:209], v[0:3]
	v_mfma_f32_16x16x32_bf16 v[44:47], v[154:157], v[186:189], v[44:47]
	v_mfma_f32_16x16x32_bf16 v[40:43], v[178:181], v[186:189], v[40:43]
	v_mfma_f32_16x16x32_bf16 v[28:31], v[154:157], v[194:197], v[28:31]
	v_mfma_f32_16x16x32_bf16 v[24:27], v[178:181], v[194:197], v[24:27]
	v_mfma_f32_16x16x32_bf16 v[12:15], v[154:157], v[202:205], v[12:15]
	v_mfma_f32_16x16x32_bf16 v[8:11], v[178:181], v[202:205], v[8:11]
	v_mfma_f32_16x16x32_bf16 v[4:7], v[154:157], v[226:229], v[4:7]
	v_mfma_f32_16x16x32_bf16 v[0:3], v[178:181], v[226:229], v[0:3]
	s_barrier
	s_add_i32 s28, s65, s49
	v_lshl_add_u64 v[166:167], s[30:31], 0, v[168:169]
	s_mov_b32 m0, s28
	ds_read_b128 v[182:185], v161 offset:16384
	ds_read_b128 v[186:189], v161 offset:17408
	ds_read_b128 v[190:193], v161 offset:18432
	ds_read_b128 v[194:197], v161 offset:19456
	ds_read_b128 v[198:201], v161 offset:20480
	ds_read_b128 v[202:205], v161 offset:21504
	ds_read_b128 v[206:209], v161 offset:22528
	ds_read_b128 v[226:229], v161 offset:23552
	global_load_lds_dwordx4 v[166:167], off
	s_add_i32 m0, s28, 0x2000
	s_add_u32 s28, s30, 0x160000
	v_lshl_add_u64 v[230:231], s[30:31], 0, v[128:129]
	s_addc_u32 s29, s31, 0
	s_add_i32 s65, s66, s49
	global_load_lds_dwordx4 v[230:231], off
	v_lshl_add_u64 v[232:233], s[28:29], 0, v[168:169]
	s_mov_b32 m0, s65
	v_lshl_add_u64 v[234:235], s[6:7], 0, v[128:129]
	global_load_lds_dwordx4 v[232:233], off
	v_lshl_add_u64 v[232:233], s[28:29], 0, v[128:129]
	s_add_i32 m0, s65, 0x2000
	s_nop 0
	global_load_lds_dwordx4 v[232:233], off
	v_lshl_add_u64 v[232:233], s[6:7], 0, v[168:169]
	s_mov_b32 m0, s50
	s_nop 0
	global_load_lds_dwordx4 v[232:233], off
	s_mov_b32 m0, s52
	s_nop 0
	global_load_lds_dwordx4 v[234:235], off
	s_waitcnt vmcnt(8)
	s_waitcnt lgkmcnt(0)
	s_barrier
	s_waitcnt lgkmcnt(0)
	v_mfma_f32_16x16x32_bf16 v[124:127], v[134:137], v[182:185], v[124:127]
	v_mfma_f32_16x16x32_bf16 v[120:123], v[142:145], v[182:185], v[120:123]
	v_mfma_f32_16x16x32_bf16 v[108:111], v[134:137], v[190:193], v[108:111]
	v_mfma_f32_16x16x32_bf16 v[104:107], v[142:145], v[190:193], v[104:107]
	v_mfma_f32_16x16x32_bf16 v[92:95], v[134:137], v[198:201], v[92:95]
	v_mfma_f32_16x16x32_bf16 v[88:91], v[142:145], v[198:201], v[88:91]
	v_mfma_f32_16x16x32_bf16 v[76:79], v[134:137], v[206:209], v[76:79]
	v_mfma_f32_16x16x32_bf16 v[72:75], v[142:145], v[206:209], v[72:75]
	v_mfma_f32_16x16x32_bf16 v[124:127], v[138:141], v[186:189], v[124:127]
	v_mfma_f32_16x16x32_bf16 v[120:123], v[146:149], v[186:189], v[120:123]
	v_mfma_f32_16x16x32_bf16 v[108:111], v[138:141], v[194:197], v[108:111]
	v_mfma_f32_16x16x32_bf16 v[104:107], v[146:149], v[194:197], v[104:107]
	v_mfma_f32_16x16x32_bf16 v[92:95], v[138:141], v[202:205], v[92:95]
	v_mfma_f32_16x16x32_bf16 v[88:91], v[146:149], v[202:205], v[88:91]
	v_mfma_f32_16x16x32_bf16 v[76:79], v[138:141], v[226:229], v[76:79]
	v_mfma_f32_16x16x32_bf16 v[72:75], v[146:149], v[226:229], v[72:75]
	v_mfma_f32_16x16x32_bf16 v[116:119], v[150:153], v[182:185], v[116:119]
	v_mfma_f32_16x16x32_bf16 v[112:115], v[162:165], v[182:185], v[112:115]
	v_mfma_f32_16x16x32_bf16 v[100:103], v[150:153], v[190:193], v[100:103]
	v_mfma_f32_16x16x32_bf16 v[96:99], v[162:165], v[190:193], v[96:99]
	v_mfma_f32_16x16x32_bf16 v[84:87], v[150:153], v[198:201], v[84:87]
	v_mfma_f32_16x16x32_bf16 v[80:83], v[162:165], v[198:201], v[80:83]
	v_mfma_f32_16x16x32_bf16 v[68:71], v[150:153], v[206:209], v[68:71]
	v_mfma_f32_16x16x32_bf16 v[56:59], v[162:165], v[206:209], v[56:59]
	v_mfma_f32_16x16x32_bf16 v[116:119], v[154:157], v[186:189], v[116:119]
	v_mfma_f32_16x16x32_bf16 v[112:115], v[178:181], v[186:189], v[112:115]
	v_mfma_f32_16x16x32_bf16 v[100:103], v[154:157], v[194:197], v[100:103]
	v_mfma_f32_16x16x32_bf16 v[96:99], v[178:181], v[194:197], v[96:99]
	v_mfma_f32_16x16x32_bf16 v[84:87], v[154:157], v[202:205], v[84:87]
	v_mfma_f32_16x16x32_bf16 v[80:83], v[178:181], v[202:205], v[80:83]
	v_mfma_f32_16x16x32_bf16 v[68:71], v[154:157], v[226:229], v[68:71]
	v_mfma_f32_16x16x32_bf16 v[56:59], v[178:181], v[226:229], v[56:59]
	s_barrier
; #define PG8_STAGE(bufoff, gbase, voff) do { _Pragma("unroll") for (int _i = 0; _i < 2; ++_i) \
;         __builtin_amdgcn_global_load_lds((const unsigned*)((const char*)(gbase) + (voff)[_i]), (PG8_LAS unsigned*)(lds + (bufoff) + ldsw + _i * 8192), 16, 0, 0); } while (0)
; #define PG8_LDA(dst, b, h) do { _Pragma("unroll") for (int m = 0; m < 4; ++m) _Pragma("unroll") for (int k = 0; k < 2; ++k) dst[m][k] = *(const PG8_LAS bf16x8*)(lds + PG8_SA(b, h) + aoff + m * 2048 + k * 1024); } while (0)
; #define PG8_LDB(dst, b, h) do { _Pragma("unroll") for (int n = 0; n < 2; ++n) _Pragma("unroll") for (int k = 0; k < 2; ++k) dst[n][k] = *(const PG8_LAS bf16x8*)(lds + PG8_SB(b, h) + boff + n * 2048 + k * 1024); } while (0)
; #define PG8_MMA(ai, bj, At, Bt) do { __builtin_amdgcn_s_setprio(1); _Pragma("unroll") for (int m = 0; m < 4; ++m) _Pragma("unroll") for (int n = 0; n < 2; ++n) _Pragma("unroll") for (int k = 0; k < 2; ++k) \
;         acc[ai][bj][m][n] = __builtin_amdgcn_mfma_f32_16x16x32_bf16(Bt[n][k], At[m][k], acc[ai][bj][m][n], 0, 0, 0); __builtin_amdgcn_s_setprio(0); } while (0)
; #define PG8_WAIT_V(n) asm volatile("s_waitcnt vmcnt(" #n ")" ::: "memory")
; #define PG8_WAIT_L(n) asm volatile("s_waitcnt lgkmcnt(" #n ")" ::: "memory")
; #define PG8_BAR __builtin_amdgcn_s_barrier()
; #define PG8_SCHED __builtin_amdgcn_sched_barrier(0)
; template <class Epi, class Sched, bool ALIGN_EPI = false, bool SP2 = false>
; __device__ __forceinline__ void gemm_phase(PG8_LAS unsigned char* lds, const Gemm g, const Sched& S, const Epi& E) {
;     ...
;             PG8_LDB(B0, 1, 0); PG8_LDB(B1, 1, 1); PG8_SCHED; PG8_LDA(At, 1, 0); PG8_STAGE(PG8_SA(0, 1), a2 + hstep, voffA);
;             PG8_WAIT_V(8); PG8_WAIT_L(0); PG8_BAR; PG8_MMA(0, 0, At, B0); PG8_MMA(0, 1, At, B1); PG8_BAR; PG8_SCHED;
	s_add_i32 s28, 0, 0x18000
	s_add_i32 s29, 0, 0x1c000
	v_add_u32_e32 v146, s28, v160
	v_add_u32_e32 v178, s29, v160
	ds_read_b128 v[134:137], v146
	ds_read_b128 v[138:141], v146 offset:1024
	ds_read_b128 v[142:145], v146 offset:2048
	ds_read_b128 v[146:149], v146 offset:3072
	ds_read_b128 v[150:153], v178
	ds_read_b128 v[154:157], v178 offset:1024
	ds_read_b128 v[162:165], v178 offset:2048
	ds_read_b128 v[178:181], v178 offset:3072
	s_add_u32 s6, s6, 0x160000
	s_addc_u32 s7, s7, 0
	s_mov_b32 m0, s53
	v_lshl_add_u64 v[236:237], s[6:7], 0, v[168:169]
	ds_read_b128 v[182:185], v161 offset:32768
	ds_read_b128 v[186:189], v161 offset:33792
	ds_read_b128 v[190:193], v161 offset:34816
	ds_read_b128 v[194:197], v161 offset:35840
	ds_read_b128 v[198:201], v161 offset:36864
	ds_read_b128 v[202:205], v161 offset:37888
	ds_read_b128 v[206:209], v161 offset:38912
	ds_read_b128 v[226:229], v161 offset:39936
	global_load_lds_dwordx4 v[236:237], off
	v_lshl_add_u64 v[236:237], s[6:7], 0, v[128:129]
	s_mov_b32 m0, s54
	s_nop 0
	global_load_lds_dwordx4 v[236:237], off
	s_waitcnt vmcnt(8)
	s_waitcnt lgkmcnt(0)
	s_barrier
	s_waitcnt lgkmcnt(0)
	v_mfma_f32_16x16x32_bf16 v[64:67], v[134:137], v[182:185], v[64:67]
	v_mfma_f32_16x16x32_bf16 v[60:63], v[142:145], v[182:185], v[60:63]
	v_mfma_f32_16x16x32_bf16 v[52:55], v[134:137], v[190:193], v[52:55]
	v_mfma_f32_16x16x32_bf16 v[48:51], v[142:145], v[190:193], v[48:51]
	v_mfma_f32_16x16x32_bf16 v[36:39], v[134:137], v[198:201], v[36:39]
	v_mfma_f32_16x16x32_bf16 v[32:35], v[142:145], v[198:201], v[32:35]
	v_mfma_f32_16x16x32_bf16 v[20:23], v[134:137], v[206:209], v[20:23]
	v_mfma_f32_16x16x32_bf16 v[16:19], v[142:145], v[206:209], v[16:19]
	v_mfma_f32_16x16x32_bf16 v[64:67], v[138:141], v[186:189], v[64:67]
	v_mfma_f32_16x16x32_bf16 v[60:63], v[146:149], v[186:189], v[60:63]
	v_mfma_f32_16x16x32_bf16 v[52:55], v[138:141], v[194:197], v[52:55]
	v_mfma_f32_16x16x32_bf16 v[48:51], v[146:149], v[194:197], v[48:51]
	v_mfma_f32_16x16x32_bf16 v[36:39], v[138:141], v[202:205], v[36:39]
	v_mfma_f32_16x16x32_bf16 v[32:35], v[146:149], v[202:205], v[32:35]
	v_mfma_f32_16x16x32_bf16 v[20:23], v[138:141], v[226:229], v[20:23]
	v_mfma_f32_16x16x32_bf16 v[16:19], v[146:149], v[226:229], v[16:19]
	v_mfma_f32_16x16x32_bf16 v[44:47], v[150:153], v[182:185], v[44:47]
	v_mfma_f32_16x16x32_bf16 v[40:43], v[162:165], v[182:185], v[40:43]
	v_mfma_f32_16x16x32_bf16 v[28:31], v[150:153], v[190:193], v[28:31]
	v_mfma_f32_16x16x32_bf16 v[24:27], v[162:165], v[190:193], v[24:27]
	v_mfma_f32_16x16x32_bf16 v[12:15], v[150:153], v[198:201], v[12:15]
	v_mfma_f32_16x16x32_bf16 v[8:11], v[162:165], v[198:201], v[8:11]
	v_mfma_f32_16x16x32_bf16 v[4:7], v[150:153], v[206:209], v[4:7]
	v_mfma_f32_16x16x32_bf16 v[0:3], v[162:165], v[206:209], v[0:3]
	v_mfma_f32_16x16x32_bf16 v[44:47], v[154:157], v[186:189], v[44:47]
	v_mfma_f32_16x16x32_bf16 v[40:43], v[178:181], v[186:189], v[40:43]
	v_mfma_f32_16x16x32_bf16 v[28:31], v[154:157], v[194:197], v[28:31]
	v_mfma_f32_16x16x32_bf16 v[24:27], v[178:181], v[194:197], v[24:27]
	v_mfma_f32_16x16x32_bf16 v[12:15], v[154:157], v[202:205], v[12:15]
	v_mfma_f32_16x16x32_bf16 v[8:11], v[178:181], v[202:205], v[8:11]
	v_mfma_f32_16x16x32_bf16 v[4:7], v[154:157], v[226:229], v[4:7]
	v_mfma_f32_16x16x32_bf16 v[0:3], v[178:181], v[226:229], v[0:3]
	s_barrier
; #define PG8_STAGE(bufoff, gbase, voff) do { _Pragma("unroll") for (int _i = 0; _i < 2; ++_i) \
;         __builtin_amdgcn_global_load_lds((const unsigned*)((const char*)(gbase) + (voff)[_i]), (PG8_LAS unsigned*)(lds + (bufoff) + ldsw + _i * 8192), 16, 0, 0); } while (0)
; #define PG8_LDA(dst, b, h) do { _Pragma("unroll") for (int m = 0; m < 4; ++m) _Pragma("unroll") for (int k = 0; k < 2; ++k) dst[m][k] = *(const PG8_LAS bf16x8*)(lds + PG8_SA(b, h) + aoff + m * 2048 + k * 1024); } while (0)
; #define PG8_MMA(ai, bj, At, Bt) do { __builtin_amdgcn_s_setprio(1); _Pragma("unroll") for (int m = 0; m < 4; ++m) _Pragma("unroll") for (int n = 0; n < 2; ++n) _Pragma("unroll") for (int k = 0; k < 2; ++k) \
;         acc[ai][bj][m][n] = __builtin_amdgcn_mfma_f32_16x16x32_bf16(Bt[n][k], At[m][k], acc[ai][bj][m][n], 0, 0, 0); __builtin_amdgcn_s_setprio(0); } while (0)
; #define PG8_WAIT_V(n) asm volatile("s_waitcnt vmcnt(" #n ")" ::: "memory")
; #define PG8_WAIT_L(n) asm volatile("s_waitcnt lgkmcnt(" #n ")" ::: "memory")
; #define PG8_BAR __builtin_amdgcn_s_barrier()
; #define PG8_SCHED __builtin_amdgcn_sched_barrier(0)
; template <class Epi, class Sched, bool ALIGN_EPI = false, bool SP2 = false>
; __device__ __forceinline__ void gemm_phase(PG8_LAS unsigned char* lds, const Gemm g, const Sched& S, const Epi& E) {
;     ...
;         for (int t = 0; t < nt; t += 2) {
;     ...
;             PG8_LDA(At, 1, 1); PG8_STAGE(PG8_SB(1, 0), b3, voffB); PG8_STAGE(PG8_SB(1, 1), b3 + hstep, voffB); PG8_STAGE(PG8_SA(1, 0), a3, voffA);
;             PG8_WAIT_V(8); PG8_WAIT_L(0); PG8_BAR; PG8_MMA(1, 0, At, B0); PG8_MMA(1, 1, At, B1); PG8_BAR; PG8_SCHED;
	s_add_i32 s6, s28, s49
	v_lshl_add_u64 v[166:167], v[166:167], 0, s[20:21]
	s_mov_b32 m0, s6
	ds_read_b128 v[182:185], v161 offset:49152
	ds_read_b128 v[186:189], v161 offset:50176
	ds_read_b128 v[190:193], v161 offset:51200
	ds_read_b128 v[194:197], v161 offset:52224
	ds_read_b128 v[198:201], v161 offset:53248
	ds_read_b128 v[202:205], v161 offset:54272
	ds_read_b128 v[206:209], v161 offset:55296
	ds_read_b128 v[226:229], v161 offset:56320
	global_load_lds_dwordx4 v[166:167], off
	s_add_i32 m0, s6, 0x2000
	s_add_u32 s6, s30, 0x160080
	v_lshl_add_u64 v[166:167], v[230:231], 0, s[20:21]
	s_addc_u32 s7, s31, 0
	s_add_i32 s28, s29, s49
	global_load_lds_dwordx4 v[166:167], off
	v_lshl_add_u64 v[166:167], s[6:7], 0, v[168:169]
	s_mov_b32 m0, s28
	s_nop 0
	global_load_lds_dwordx4 v[166:167], off
	v_lshl_add_u64 v[166:167], s[6:7], 0, v[128:129]
	s_add_i32 m0, s28, 0x2000
	s_nop 0
	global_load_lds_dwordx4 v[166:167], off
	v_lshl_add_u64 v[166:167], v[232:233], 0, s[20:21]
	s_mov_b32 m0, s58
	s_nop 0
	global_load_lds_dwordx4 v[166:167], off
	v_lshl_add_u64 v[166:167], v[234:235], 0, s[20:21]
	s_mov_b32 m0, s59
	s_nop 0
	global_load_lds_dwordx4 v[166:167], off
	s_waitcnt vmcnt(8)
	s_waitcnt lgkmcnt(0)
	s_barrier
	s_waitcnt lgkmcnt(0)
	v_mfma_f32_16x16x32_bf16 v[124:127], v[134:137], v[182:185], v[124:127]
	v_mfma_f32_16x16x32_bf16 v[120:123], v[142:145], v[182:185], v[120:123]
	v_mfma_f32_16x16x32_bf16 v[108:111], v[134:137], v[190:193], v[108:111]
	v_mfma_f32_16x16x32_bf16 v[104:107], v[142:145], v[190:193], v[104:107]
	v_mfma_f32_16x16x32_bf16 v[92:95], v[134:137], v[198:201], v[92:95]
	v_mfma_f32_16x16x32_bf16 v[88:91], v[142:145], v[198:201], v[88:91]
	v_mfma_f32_16x16x32_bf16 v[76:79], v[134:137], v[206:209], v[76:79]
	v_mfma_f32_16x16x32_bf16 v[72:75], v[142:145], v[206:209], v[72:75]
	v_mfma_f32_16x16x32_bf16 v[124:127], v[138:141], v[186:189], v[124:127]
	v_mfma_f32_16x16x32_bf16 v[120:123], v[146:149], v[186:189], v[120:123]
	v_mfma_f32_16x16x32_bf16 v[108:111], v[138:141], v[194:197], v[108:111]
	v_mfma_f32_16x16x32_bf16 v[104:107], v[146:149], v[194:197], v[104:107]
	v_mfma_f32_16x16x32_bf16 v[92:95], v[138:141], v[202:205], v[92:95]
	v_mfma_f32_16x16x32_bf16 v[88:91], v[146:149], v[202:205], v[88:91]
	v_mfma_f32_16x16x32_bf16 v[76:79], v[138:141], v[226:229], v[76:79]
	v_mfma_f32_16x16x32_bf16 v[72:75], v[146:149], v[226:229], v[72:75]
	v_mfma_f32_16x16x32_bf16 v[116:119], v[150:153], v[182:185], v[116:119]
	v_mfma_f32_16x16x32_bf16 v[112:115], v[162:165], v[182:185], v[112:115]
	v_mfma_f32_16x16x32_bf16 v[100:103], v[150:153], v[190:193], v[100:103]
	v_mfma_f32_16x16x32_bf16 v[96:99], v[162:165], v[190:193], v[96:99]
	v_mfma_f32_16x16x32_bf16 v[84:87], v[150:153], v[198:201], v[84:87]
	v_mfma_f32_16x16x32_bf16 v[80:83], v[162:165], v[198:201], v[80:83]
	v_mfma_f32_16x16x32_bf16 v[68:71], v[150:153], v[206:209], v[68:71]
	v_mfma_f32_16x16x32_bf16 v[56:59], v[162:165], v[206:209], v[56:59]
	v_mfma_f32_16x16x32_bf16 v[116:119], v[154:157], v[186:189], v[116:119]
	v_mfma_f32_16x16x32_bf16 v[112:115], v[178:181], v[186:189], v[112:115]
	v_mfma_f32_16x16x32_bf16 v[100:103], v[154:157], v[194:197], v[100:103]
	v_mfma_f32_16x16x32_bf16 v[96:99], v[178:181], v[194:197], v[96:99]
	v_mfma_f32_16x16x32_bf16 v[84:87], v[154:157], v[202:205], v[84:87]
	v_mfma_f32_16x16x32_bf16 v[80:83], v[178:181], v[202:205], v[80:83]
	v_mfma_f32_16x16x32_bf16 v[68:71], v[154:157], v[226:229], v[68:71]
	v_mfma_f32_16x16x32_bf16 v[56:59], v[178:181], v[226:229], v[56:59]
	s_barrier
	s_add_u32 s9, s9, 0x100
	s_addc_u32 s44, s44, 0
	s_cmp_ge_u32 s45, s43
	s_mov_b64 s[28:29], s[34:35]
	s_mov_b32 s6, s45
	s_cbranch_scc0 .LBB0_917
	s_setprio 0
	s_and_b64 vcc, exec, s[22:23]
	s_cbranch_vccz .LBB0_920
	s_barrier
